# hand-written software-pipelined selected-block attention stream (LDS-DMA rings, conflict-free swizzle) + ds_read2_b64 split
# speedup vs baseline: 1.0193x; 1.0193x over previous
.LBB0_148:
	s_lshl_b32 s2, s3, 6
	s_add_i32 s3, s61, s0
	v_add3_u32 v2, s3, v229, v230
	s_waitcnt lgkmcnt(8)
	ds_read_b128 v[92:95], v2
	s_waitcnt lgkmcnt(8)
	ds_read_b128 v[88:91], v2 offset:64
	s_waitcnt lgkmcnt(8)
	ds_read_b128 v[84:87], v2 offset:2304
	s_waitcnt lgkmcnt(8)
	ds_read_b128 v[80:83], v2 offset:2368
	s_waitcnt lgkmcnt(8)
	ds_read_b128 v[76:79], v2 offset:4608
	s_waitcnt lgkmcnt(8)
	ds_read_b128 v[72:75], v2 offset:4672
	s_waitcnt lgkmcnt(8)
	ds_read_b128 v[68:71], v2 offset:6912
	s_waitcnt lgkmcnt(8)
	ds_read_b128 v[64:67], v2 offset:6976
	s_or_b32 s14, s2, 63
	s_max_u32 s14, s2, s14
	v_add3_u32 v2, s3, v232, v230
	v_cmp_ge_u32_e32 vcc, s14, v174
	v_add_u32_e32 v236, s2, v233
	v_add_u32_e32 v240, 0x2000, v2
	v_add_u32_e32 v239, 0x2800, v2
	v_add_u32_e32 v238, 0x3000, v2
	v_add_u32_e32 v237, 0x3800, v2
	s_cbranch_vccz .LBB0_153
	v_add_u32_e32 v2, s2, v231
	v_or_b32_e32 v3, 1, v2
	v_cmp_lt_u32_e64 s[56:57], v3, v174
	v_or_b32_e32 v3, 2, v2
	v_cmp_lt_u32_e64 s[54:55], v3, v174
	v_or_b32_e32 v3, 3, v2
	v_cmp_lt_u32_e64 s[50:51], v3, v174
	v_add_u32_e32 v3, 16, v2
	s_waitcnt lgkmcnt(7)
	v_mfma_f32_16x16x32_bf16 v[96:99], v[92:95], v[4:7], v[20:23]
	v_cmp_lt_u32_e64 s[52:53], v3, v174
	v_add_u32_e32 v3, 17, v2
	v_cmp_lt_u32_e64 s[48:49], v3, v174
	v_add_u32_e32 v3, 18, v2
	v_cmp_lt_u32_e64 s[46:47], v3, v174
	v_add_u32_e32 v3, 19, v2
	v_cmp_lt_u32_e64 s[42:43], v3, v174
	v_add_u32_e32 v3, 32, v2
	s_waitcnt lgkmcnt(6)
	v_mfma_f32_16x16x32_bf16 v[96:99], v[88:91], v[8:11], v[96:99]
	v_cmp_lt_u32_e64 s[44:45], v3, v174
	v_add_u32_e32 v3, 33, v2
	v_cmp_lt_u32_e64 s[40:41], v3, v174
	v_add_u32_e32 v3, 34, v2
	v_cmp_lt_u32_e64 s[38:39], v3, v174
	v_add_u32_e32 v3, 35, v2
	v_cmp_lt_u32_e32 vcc, v3, v174
	s_nop 0
	v_exp_f32_e32 v3, v96
	v_cmp_lt_u32_e64 s[58:59], v2, v174
	s_waitcnt lgkmcnt(5)
	v_mfma_f32_16x16x32_bf16 v[100:103], v[84:87], v[4:7], v[20:23]
	v_cndmask_b32_e64 v96, 0, v3, s[58:59]
	v_exp_f32_e32 v3, v97
	s_waitcnt lgkmcnt(4)
	v_mfma_f32_16x16x32_bf16 v[100:103], v[80:83], v[8:11], v[100:103]
	v_fma_f32 v249, v182, v96, 0
	v_cndmask_b32_e64 v97, 0, v3, s[56:57]
	v_exp_f32_e32 v3, v98
	s_waitcnt lgkmcnt(3)
	v_mfma_f32_16x16x32_bf16 v[104:107], v[76:79], v[4:7], v[20:23]
	v_fma_f32 v250, v182, v97, 0
	v_cndmask_b32_e64 v98, 0, v3, s[54:55]
	v_exp_f32_e32 v3, v99
	s_waitcnt lgkmcnt(2)
	v_mfma_f32_16x16x32_bf16 v[104:107], v[72:75], v[8:11], v[104:107]
	v_fma_f32 v251, v182, v98, 0
	v_cndmask_b32_e64 v99, 0, v3, s[50:51]
	v_exp_f32_e32 v3, v100
	s_waitcnt lgkmcnt(1)
	v_mfma_f32_16x16x32_bf16 v[108:111], v[68:71], v[4:7], v[20:23]
	v_fma_f32 v248, v182, v99, 0
	v_cndmask_b32_e64 v100, 0, v3, s[52:53]
	v_exp_f32_e32 v3, v101
	s_waitcnt lgkmcnt(0)
	v_mfma_f32_16x16x32_bf16 v[108:111], v[64:67], v[8:11], v[108:111]
	v_fma_f32 v245, v182, v100, 0
	v_cndmask_b32_e64 v101, 0, v3, s[48:49]
	v_exp_f32_e32 v3, v102
	v_fma_f32 v246, v182, v101, 0
	s_nop 3
	v_exp_f32_e32 v115, v108
	v_mul_f32_e32 v108, v182, v96
	v_cndmask_b32_e64 v102, 0, v3, s[46:47]
	v_exp_f32_e32 v3, v103
	v_mul_f32_e32 v96, v182, v97
	v_mul_f32_e32 v97, v182, v98
	v_mul_f32_e32 v98, v182, v99
	v_cndmask_b32_e64 v103, 0, v3, s[42:43]
	v_exp_f32_e32 v3, v104
	v_mul_f32_e32 v99, v182, v100
	v_mul_f32_e32 v100, v182, v101
	v_mul_f32_e32 v101, v182, v102
	v_cndmask_b32_e64 v104, 0, v3, s[44:45]
	v_exp_f32_e32 v3, v105
	v_fma_f32 v247, v182, v102, 0
	v_mul_f32_e32 v102, v182, v103
	v_fma_f32 v241, v182, v103, 0
	v_cndmask_b32_e64 v105, 0, v3, s[40:41]
	v_exp_f32_e32 v3, v106
	v_mul_f32_e32 v103, v182, v104
	v_fma_f32 v131, v182, v104, 0
	v_mul_f32_e32 v104, v182, v105
	v_cndmask_b32_e64 v106, 0, v3, s[38:39]
	v_exp_f32_e32 v3, v107
	v_fma_f32 v242, v182, v105, 0
	v_mul_f32_e32 v105, v182, v106
	v_fma_f32 v243, v182, v106, 0
	v_cndmask_b32_e32 v107, 0, v3, vcc
	v_mul_f32_e32 v106, v182, v107
	v_exp_f32_e32 v114, v109
	v_exp_f32_e32 v130, v110
	v_exp_f32_e32 v3, v111
	v_fma_f32 v244, v182, v107, 0
	v_cvt_pk_bf16_f32 v96, v108, v96
	v_cvt_pk_bf16_f32 v97, v97, v98
	v_cvt_pk_bf16_f32 v98, v99, v100
	v_cvt_pk_bf16_f32 v99, v101, v102
	v_cvt_pk_bf16_f32 v108, v103, v104
	v_cvt_pk_bf16_f32 v109, v105, v106
	v_mfma_f32_16x16x32_bf16 v[100:103], v[92:95], v[12:15], v[20:23]
	v_mfma_f32_16x16x32_bf16 v[104:107], v[84:87], v[12:15], v[20:23]
	v_mfma_f32_16x16x32_bf16 v[110:113], v[76:79], v[12:15], v[20:23]
	s_waitcnt vmcnt(0)
	v_mfma_f32_16x16x32_bf16 v[100:103], v[88:91], v[16:19], v[100:103]
	v_mfma_f32_16x16x32_bf16 v[104:107], v[80:83], v[16:19], v[104:107]
	v_mfma_f32_16x16x32_bf16 v[110:113], v[72:75], v[16:19], v[110:113]
	s_nop 5
	v_exp_f32_e32 v100, v100
	v_exp_f32_e32 v101, v101
	v_exp_f32_e32 v102, v102
	v_mfma_f32_16x16x32_bf16 v[116:119], v[68:71], v[12:15], v[20:23]
	v_exp_f32_e32 v103, v103
	v_exp_f32_e32 v104, v104
	v_exp_f32_e32 v105, v105
	v_exp_f32_e32 v106, v106
	v_exp_f32_e32 v107, v107
	v_exp_f32_e32 v110, v110
	v_exp_f32_e32 v111, v111
	v_mfma_f32_16x16x32_bf16 v[116:119], v[64:67], v[16:19], v[116:119]
	v_exp_f32_e32 v112, v112
	v_exp_f32_e32 v113, v113
	v_cndmask_b32_e64 v100, 0, v100, s[58:59]
	v_cndmask_b32_e64 v101, 0, v101, s[56:57]
	v_cndmask_b32_e64 v102, 0, v102, s[54:55]
	v_cndmask_b32_e64 v103, 0, v103, s[50:51]
	v_cndmask_b32_e64 v104, 0, v104, s[52:53]
	v_cndmask_b32_e64 v105, 0, v105, s[48:49]
	v_cndmask_b32_e64 v106, 0, v106, s[46:47]
	v_cndmask_b32_e64 v107, 0, v107, s[42:43]
	v_cndmask_b32_e64 v110, 0, v110, s[44:45]
	v_cndmask_b32_e64 v111, 0, v111, s[40:41]
	v_cndmask_b32_e64 v112, 0, v112, s[38:39]
	v_cndmask_b32_e32 v113, 0, v113, vcc
	v_exp_f32_e32 v198, v116
	v_exp_f32_e32 v199, v117
	v_mul_f32_e32 v116, v183, v100
	v_fmac_f32_e32 v249, v183, v100
	v_mul_f32_e32 v100, v183, v101
	v_fmac_f32_e32 v250, v183, v101
	v_mul_f32_e32 v101, v183, v102
	v_fmac_f32_e32 v251, v183, v102
	v_mul_f32_e32 v102, v183, v103
	v_fmac_f32_e32 v248, v183, v103
	v_mul_f32_e32 v103, v183, v104
	v_fmac_f32_e32 v245, v183, v104
	v_mul_f32_e32 v104, v183, v105
	v_fmac_f32_e32 v246, v183, v105
	v_mul_f32_e32 v105, v183, v106
	v_fmac_f32_e32 v247, v183, v106
	v_mul_f32_e32 v106, v183, v107
	v_fmac_f32_e32 v241, v183, v107
	v_mul_f32_e32 v107, v183, v110
	v_mul_f32_e32 v117, v183, v111
	v_exp_f32_e32 v252, v118
	v_exp_f32_e32 v193, v119
	v_mul_f32_e32 v118, v183, v112
	v_fmac_f32_e32 v243, v183, v112
	v_mul_f32_e32 v119, v183, v113
	v_fmac_f32_e32 v244, v183, v113
	v_cvt_pk_bf16_f32 v112, v103, v104
	v_cvt_pk_bf16_f32 v113, v105, v106
	v_cvt_pk_bf16_f32 v128, v107, v117
	ds_read_b64 v[104:105], v240 offset:1024
	ds_read_b64 v[106:107], v240 offset:1056
	ds_read_b64 v[120:121], v239 offset:1280
	ds_read_b64 v[122:123], v239 offset:1312
	ds_read_b64 v[132:133], v238 offset:1536
	ds_read_b64 v[134:135], v238 offset:1568
	ds_read_b64 v[140:141], v237 offset:1792
	ds_read_b64 v[142:143], v237 offset:1824
	v_fmac_f32_e32 v131, v183, v110
	v_fmac_f32_e32 v242, v183, v111
	v_cvt_pk_bf16_f32 v110, v116, v100
	v_cvt_pk_bf16_f32 v111, v101, v102
	v_cvt_pk_bf16_f32 v129, v118, v119
	s_waitcnt lgkmcnt(6)
	v_mfma_f32_16x16x32_bf16 v[100:103], v[104:107], v[96:99], v[60:63]
	v_mfma_f32_16x16x32_bf16 v[104:107], v[104:107], v[110:113], v[56:59]
	s_waitcnt lgkmcnt(4)
	v_mfma_f32_16x16x32_bf16 v[116:119], v[120:123], v[96:99], v[52:55]
	v_mfma_f32_16x16x32_bf16 v[120:123], v[120:123], v[110:113], v[48:51]
	s_waitcnt lgkmcnt(2)
	v_mfma_f32_16x16x32_bf16 v[124:127], v[132:135], v[96:99], v[44:47]
	v_mfma_f32_16x16x32_bf16 v[132:135], v[132:135], v[110:113], v[40:43]
	s_waitcnt lgkmcnt(0)
	v_mfma_f32_16x16x32_bf16 v[136:139], v[140:143], v[96:99], v[36:39]
	ds_read_b64 v[96:97], v240 offset:1088
	ds_read_b64 v[98:99], v240 offset:1120
	ds_read_b64 v[152:153], v239 offset:1344
	ds_read_b64 v[154:155], v239 offset:1376
	ds_read_b64 v[148:149], v238 offset:1600
	ds_read_b64 v[150:151], v238 offset:1632
	ds_read_b64 v[144:145], v237 offset:1856
	ds_read_b64 v[146:147], v237 offset:1888
	v_mfma_f32_16x16x32_bf16 v[140:143], v[140:143], v[110:113], v[32:35]
	v_add_f32_e32 v110, v249, v250
	v_add_f32_e32 v111, v251, v248
	v_add_f32_e32 v110, v110, v111
	ds_bpermute_b32 v111, v234, v248
	ds_bpermute_b32 v112, v234, v235
	v_add_f32_e32 v113, v247, v241
	s_waitcnt lgkmcnt(0)
	v_cndmask_b32_e64 v112, v111, v112, s[36:37]
	v_add_f32_e32 v110, v110, v112
	v_add_f32_e32 v112, v245, v246
	v_add_f32_e32 v112, v112, v113
	ds_bpermute_b32 v113, v234, v241
	ds_bpermute_b32 v241, v234, v244
	s_waitcnt lgkmcnt(1)
	v_cndmask_b32_e64 v111, v113, v111, s[36:37]
	v_add_f32_e32 v111, v112, v111
	ds_write2_b32 v236, v110, v111 offset1:4
	v_add_f32_e32 v110, v131, v242
	v_add_f32_e32 v111, v243, v244
	v_add_f32_e32 v110, v110, v111
	s_waitcnt lgkmcnt(1)
	v_cndmask_b32_e64 v111, v241, v113, s[36:37]
	v_add_f32_e32 v110, v110, v111
	ds_write_b32 v236, v110 offset:32
	v_add_u32_e32 v110, 50, v2
	v_add_u32_e32 v111, 48, v2
	v_cmp_lt_u32_e64 s[38:39], v110, v171
	v_add_u32_e32 v110, 49, v2
	v_add_u32_e32 v2, 51, v2
	v_cmp_lt_u32_e32 vcc, v111, v174
	v_cmp_lt_u32_e64 s[40:41], v2, v171
	v_cmp_lt_u32_e64 s[42:43], v110, v174
	v_cndmask_b32_e64 v111, 0, v130, s[38:39]
	v_cndmask_b32_e32 v110, 0, v115, vcc
	v_cndmask_b32_e64 v2, 0, v114, s[42:43]
	v_cndmask_b32_e64 v3, 0, v3, s[40:41]
	v_pk_mul_f32 v[112:113], v[184:185], v[110:111]
	v_pk_fma_f32 v[114:115], v[184:185], v[110:111], 0 op_sel_hi:[1,1,0]
	v_pk_mul_f32 v[110:111], v[184:185], v[2:3]
	v_cndmask_b32_e64 v130, 0, v199, s[42:43]
	v_cvt_pk_bf16_f32 v110, v112, v110
	v_cvt_pk_bf16_f32 v111, v113, v111
	v_cndmask_b32_e64 v113, 0, v252, s[38:39]
	v_cndmask_b32_e32 v112, 0, v198, vcc
	v_cndmask_b32_e64 v131, 0, v193, s[40:41]
	v_pk_fma_f32 v[2:3], v[184:185], v[2:3], 0 op_sel_hi:[1,1,0]
	v_pk_mul_f32 v[198:199], v[186:187], v[112:113]
	v_pk_fma_f32 v[242:243], v[186:187], v[112:113], v[114:115]
	v_pk_mul_f32 v[112:113], v[186:187], v[130:131]
	v_pk_fma_f32 v[2:3], v[186:187], v[130:131], v[2:3]
	v_cvt_pk_bf16_f32 v130, v198, v112
	v_cvt_pk_bf16_f32 v131, v199, v113
	v_mfma_f32_16x16x32_bf16 v[112:115], v[96:99], v[108:111], v[100:103]
	s_nop 0
	v_mfma_f32_16x16x32_bf16 v[96:99], v[96:99], v[128:131], v[104:107]
	v_mfma_f32_16x16x32_bf16 v[116:119], v[152:155], v[108:111], v[116:119]
	v_mfma_f32_16x16x32_bf16 v[100:103], v[152:155], v[128:131], v[120:123]
	v_mfma_f32_16x16x32_bf16 v[120:123], v[148:151], v[108:111], v[124:127]
	v_mfma_f32_16x16x32_bf16 v[104:107], v[148:151], v[128:131], v[132:135]
	v_mfma_f32_16x16x32_bf16 v[124:127], v[144:147], v[108:111], v[136:139]
	v_mfma_f32_16x16x32_bf16 v[108:111], v[144:147], v[128:131], v[140:143]
	v_add_f32_e64 v128, v242, v2
	v_add_f32_e64 v129, v243, v3
	v_add_f32_e32 v2, v128, v129
	ds_bpermute_b32 v128, v234, v3
	s_waitcnt lgkmcnt(0)
	v_cndmask_b32_e64 v128, v128, v241, s[36:37]
	s_cbranch_execnz .LBB0_151
.LBB0_150:
	s_waitcnt lgkmcnt(7)
	v_mfma_f32_16x16x32_bf16 v[96:99], v[92:95], v[4:7], v[20:23]
	s_waitcnt lgkmcnt(5)
	v_mfma_f32_16x16x32_bf16 v[100:103], v[84:87], v[4:7], v[20:23]
	v_mfma_f32_16x16x32_bf16 v[96:99], v[88:91], v[8:11], v[96:99]
	s_waitcnt lgkmcnt(4)
	v_mfma_f32_16x16x32_bf16 v[100:103], v[80:83], v[8:11], v[100:103]
	s_waitcnt lgkmcnt(3)
	v_mfma_f32_16x16x32_bf16 v[104:107], v[76:79], v[4:7], v[20:23]
	s_nop 3
	v_exp_f32_e32 v108, v96
	v_exp_f32_e32 v109, v97
	v_exp_f32_e32 v110, v98
	v_exp_f32_e32 v111, v99
	v_exp_f32_e32 v112, v100
	v_exp_f32_e32 v113, v101
	s_waitcnt lgkmcnt(2)
	v_mfma_f32_16x16x32_bf16 v[96:99], v[72:75], v[8:11], v[104:107]
	s_nop 2
	v_exp_f32_e32 v104, v102
	v_exp_f32_e32 v105, v103
	s_waitcnt lgkmcnt(1)
	v_mfma_f32_16x16x32_bf16 v[100:103], v[68:71], v[4:7], v[20:23]
	s_nop 0
	v_exp_f32_e32 v106, v96
	v_exp_f32_e32 v107, v97
	v_exp_f32_e32 v115, v98
	v_exp_f32_e32 v114, v99
	s_waitcnt lgkmcnt(0)
	v_mfma_f32_16x16x32_bf16 v[96:99], v[64:67], v[8:11], v[100:103]
	v_mul_f32_e64 v104, v184, v104
	v_mul_f32_e64 v105, v185, v105
	v_mul_f32_e32 v121, v182, v115
	v_fma_f32 v122, v182, v115, 0
	v_mfma_f32_16x16x32_bf16 v[92:95], v[92:95], v[12:15], v[20:23]
	v_mul_f32_e64 v100, v184, v110
	v_mul_f32_e64 v101, v185, v111
	s_nop 0
	v_exp_f32_e32 v97, v97
	v_exp_f32_e32 v2, v96
	v_mfma_f32_16x16x32_bf16 v[84:87], v[84:87], v[12:15], v[20:23]
	v_exp_f32_e32 v3, v98
	v_exp_f32_e32 v96, v99
	v_pk_mul_f32 v[98:99], v[184:185], v[108:109]
	v_mfma_f32_16x16x32_bf16 v[76:79], v[76:79], v[12:15], v[20:23]
	v_mul_f32_e32 v108, v182, v97
	v_add_f32_e32 v109, 0, v98
	v_add_f32_e32 v116, 0, v99
	v_mfma_f32_16x16x32_bf16 v[68:71], v[68:71], v[12:15], v[20:23]
	v_add_f32_e32 v110, 0, v100
	v_add_f32_e32 v111, 0, v101
	v_pk_mul_f32 v[102:103], v[184:185], v[112:113]
	s_waitcnt vmcnt(0)
	v_mfma_f32_16x16x32_bf16 v[88:91], v[88:91], v[16:19], v[92:95]
	v_add_f32_e32 v117, 0, v104
	v_add_f32_e32 v118, 0, v105
	v_add_f32_e32 v112, 0, v102
	v_mfma_f32_16x16x32_bf16 v[80:83], v[80:83], v[16:19], v[84:87]
	v_cvt_pk_bf16_f32 v92, v98, v99
	v_cvt_pk_bf16_f32 v93, v100, v101
	v_cvt_pk_bf16_f32 v94, v102, v103
	v_mfma_f32_16x16x32_bf16 v[72:75], v[72:75], v[16:19], v[76:79]
	v_exp_f32_e32 v86, v88
	v_exp_f32_e32 v87, v89
	v_cvt_pk_bf16_f32 v95, v104, v105
	v_mfma_f32_16x16x32_bf16 v[64:67], v[64:67], v[16:19], v[68:71]
	v_exp_f32_e32 v76, v90
	v_exp_f32_e32 v78, v80
	v_exp_f32_e32 v79, v81
	v_exp_f32_e32 v80, v82
	v_exp_f32_e32 v81, v83
	v_exp_f32_e32 v82, v72
	v_exp_f32_e32 v83, v73
	v_exp_f32_e32 v85, v74
	v_exp_f32_e32 v115, v75
	v_exp_f32_e32 v88, v64
	v_exp_f32_e32 v90, v65
	v_exp_f32_e32 v89, v66
	v_exp_f32_e32 v97, v67
	ds_read_b64 v[64:65], v240 offset:1024
	ds_read_b64 v[66:67], v240 offset:1056
	ds_read_b64 v[72:73], v239 offset:1280
	ds_read_b64 v[74:75], v239 offset:1312
	v_exp_f32_e32 v77, v91
	v_pk_mul_f32 v[68:69], v[186:187], v[86:87]
	s_waitcnt lgkmcnt(2)
	v_mfma_f32_16x16x32_bf16 v[60:63], v[64:67], v[92:95], v[60:63]
	v_mul_f32_e64 v70, v186, v76
	v_mul_f32_e64 v71, v187, v77
	v_pk_mul_f32 v[76:77], v[186:187], v[78:79]
	v_pk_mul_f32 v[78:79], v[186:187], v[80:81]
	v_add_f32_e32 v86, v109, v68
	v_add_f32_e32 v87, v116, v69
	v_add_f32_e32 v91, v110, v70
	v_add_f32_e32 v98, v111, v71
	v_cvt_pk_bf16_f32 v68, v68, v69
	v_cvt_pk_bf16_f32 v69, v70, v71
	v_cvt_pk_bf16_f32 v70, v76, v77
	v_cvt_pk_bf16_f32 v71, v78, v79
	s_waitcnt lgkmcnt(0)
	v_mfma_f32_16x16x32_bf16 v[52:55], v[72:75], v[92:95], v[52:55]
	v_add_f32_e32 v113, 0, v103
	v_pk_mul_f32 v[106:107], v[184:185], v[106:107]
	v_add_f32_e32 v101, v117, v78
	v_mfma_f32_16x16x32_bf16 v[56:59], v[64:67], v[68:71], v[56:59]
	ds_read_b64 v[64:65], v238 offset:1536
	ds_read_b64 v[66:67], v238 offset:1568
	v_add_f32_e32 v102, v118, v79
	v_pk_mul_f32 v[78:79], v[182:183], v[114:115]
	v_mfma_f32_16x16x32_bf16 v[48:51], v[72:75], v[68:71], v[48:51]
	ds_read_b64 v[72:73], v237 offset:1792
	ds_read_b64 v[74:75], v237 offset:1824
	v_add_f32_e32 v119, 0, v106
	v_add_f32_e32 v120, 0, v107
	s_waitcnt lgkmcnt(2)
	v_mfma_f32_16x16x32_bf16 v[44:47], v[64:67], v[92:95], v[44:47]
	v_add_f32_e32 v99, v112, v76
	v_add_f32_e32 v100, v113, v77
	v_pk_mul_f32 v[76:77], v[186:187], v[82:83]
	v_mfma_f32_16x16x32_bf16 v[40:43], v[64:67], v[68:71], v[40:43]
	ds_bpermute_b32 v66, v234, v235
	v_mul_f32_e32 v80, v183, v85
	v_add_f32_e32 v81, 0, v78
	s_waitcnt lgkmcnt(1)
	v_mfma_f32_16x16x32_bf16 v[36:39], v[72:75], v[92:95], v[36:39]
	ds_bpermute_b32 v94, v234, v98
	v_add_f32_e32 v67, v86, v87
	v_add_f32_e32 v86, v91, v98
	v_add_f32_e32 v103, v119, v76
	v_add_f32_e32 v104, v120, v77
	v_fmac_f32_e32 v122, v183, v85
	v_cvt_pk_bf16_f32 v85, v121, v78
	v_add_f32_e32 v105, v81, v79
	v_cvt_pk_bf16_f32 v64, v76, v77
	v_cvt_pk_bf16_f32 v65, v80, v79
	v_mfma_f32_16x16x32_bf16 v[32:35], v[72:75], v[68:71], v[32:35]
	ds_read_b64 v[68:69], v240 offset:1088
	ds_read_b64 v[70:71], v240 offset:1120
	ds_read_b64 v[72:73], v239 offset:1344
	ds_read_b64 v[74:75], v239 offset:1376
	ds_read_b64 v[76:77], v238 offset:1600
	ds_read_b64 v[78:79], v238 offset:1632
	v_add_f32_e32 v67, v67, v86
	s_waitcnt lgkmcnt(6)
	v_cndmask_b32_e64 v66, v94, v66, s[36:37]
	v_pk_mul_f32 v[92:93], v[182:183], v[96:97]
	v_add_f32_e32 v91, v67, v66
	v_pk_mul_f32 v[66:67], v[184:185], v[2:3]
	v_cvt_pk_bf16_f32 v84, v106, v107
	v_cvt_pk_bf16_f32 v86, v66, v108
	v_pk_mov_b32 v[66:67], v[66:67], v[92:93] op_sel:[1,0]
	ds_read_b64 v[80:81], v237 offset:1856
	ds_read_b64 v[82:83], v237 offset:1888
	v_cvt_pk_bf16_f32 v87, v66, v67
	ds_bpermute_b32 v106, v234, v102
	v_mul_f32_e32 v90, v183, v90
	s_waitcnt lgkmcnt(5)
	v_mfma_f32_16x16x32_bf16 v[116:119], v[72:75], v[84:87], v[52:55]
	v_add_f32_e32 v95, v99, v100
	v_add_f32_e32 v100, v101, v102
	v_mov_b32_e32 v109, v92
	ds_bpermute_b32 v52, v234, v105
	v_mfma_f32_16x16x32_bf16 v[112:115], v[68:71], v[84:87], v[60:63]
	v_add_f32_e32 v53, v103, v104
	s_nop 1
	v_pk_mul_f32 v[60:61], v[186:187], v[88:89]
	s_waitcnt lgkmcnt(2)
	v_mfma_f32_16x16x32_bf16 v[124:127], v[80:83], v[84:87], v[36:39]
	v_cvt_pk_bf16_f32 v66, v60, v90
	v_cvt_pk_bf16_f32 v67, v61, v93
	s_nop 1
	v_mfma_f32_16x16x32_bf16 v[96:99], v[68:71], v[64:67], v[56:59]
	s_nop 2
	v_add_f32_e32 v56, v95, v100
	v_mfma_f32_16x16x32_bf16 v[100:103], v[72:75], v[64:67], v[48:51]
	s_waitcnt lgkmcnt(1)
	v_cndmask_b32_e64 v57, v106, v94, s[36:37]
	v_add_f32_e32 v56, v56, v57
	ds_write2_b32 v236, v91, v56 offset1:4
	v_add_f32_e32 v48, v122, v105
	v_add_f32_e32 v48, v53, v48
	s_waitcnt lgkmcnt(1)
	v_cndmask_b32_e64 v49, v52, v106, s[36:37]
	v_mfma_f32_16x16x32_bf16 v[120:123], v[76:79], v[84:87], v[44:47]
	v_mov_b32_e32 v91, v93
	s_nop 1
	v_add_f32_e32 v44, v48, v49
	ds_write_b32 v236, v44 offset:32
	v_pk_fma_f32 v[44:45], v[184:185], v[2:3], 0 op_sel_hi:[1,1,0]
	v_pk_add_f32 v[2:3], v[108:109], 0 op_sel_hi:[1,0]
	v_mfma_f32_16x16x32_bf16 v[104:107], v[76:79], v[64:67], v[40:43]
	v_add_f32_e64 v2, v2, v90
	v_add_f32_e64 v3, v3, v91
	ds_bpermute_b32 v38, v234, v3
	v_pk_fma_f32 v[36:37], v[186:187], v[88:89], v[44:45]
	v_mfma_f32_16x16x32_bf16 v[108:111], v[80:83], v[64:67], v[32:35]
	s_waitcnt lgkmcnt(0)
	v_cndmask_b32_e64 v128, v38, v52, s[36:37]
	s_nop 0
	v_pk_add_f32 v[32:33], v[36:37], v[2:3]
	s_nop 0
	v_add_f32_e32 v2, v32, v33

.LBB0_161:
	v_mov_b32_e32 v128, v172
	v_readlane_b32 s2, v254, 49
	s_waitcnt lgkmcnt(0)
	s_barrier
	ds_read_b128 v[20:23], v223
	v_readlane_b32 s3, v254, 50
	v_ashrrev_i32_e32 v129, 31, v128
	s_waitcnt vmcnt(1)
	v_mov_b64_e32 v[24:25], s[10:11]
	v_lshl_add_u64 v[2:3], s[2:3], 0, v[128:129]
	s_mul_i32 s94, s94, 12
	v_mad_u64_u32 v[24:25], s[2:3], v2, s23, v[24:25]
	v_mad_i32_i24 v25, v3, s23, v25
	s_lshl_b32 s14, s94, 1
	s_mov_b32 s15, s1
	v_readlane_b32 s2, v254, 47
	v_lshl_add_u64 v[2:3], v[24:25], 0, s[14:15]
	v_readlane_b32 s3, v254, 48
	s_lshl_b32 s0, s92, 21
	s_nop 0
	v_lshl_add_u64 v[130:131], s[2:3], 1, v[2:3]
	global_load_ushort v0, v[130:131], off offset:2560
	s_waitcnt vmcnt(0)
	v_lshlrev_b32_e32 v0, 16, v0
	v_mul_f32_e32 v0, 0xbfb8aa3b, v0
	v_exp_f32_e32 v0, v0
	s_nop 0
	v_add_f32_e32 v0, 1.0, v0
	v_div_scale_f32 v2, s[2:3], v0, v0, 1.0
	v_rcp_f32_e32 v3, v2
	s_nop 0
	v_fma_f32 v24, -v2, v3, 1.0
	v_fmac_f32_e32 v3, v24, v3
	v_div_scale_f32 v24, vcc, 1.0, v0, 1.0
	v_mul_f32_e32 v25, v24, v3
	v_fma_f32 v26, -v2, v25, v24
	v_fmac_f32_e32 v25, v26, v3
	v_fma_f32 v2, -v2, v25, v24
	v_div_fmas_f32 v2, v2, v3, v25
	v_div_fixup_f32 v0, v2, v0, 1.0
	v_pk_mul_f32 v[26:27], v[114:115], v[0:1] op_sel_hi:[1,0]
	v_pk_mul_f32 v[24:25], v[112:113], v[0:1] op_sel_hi:[1,0]
	ds_write_b128 v224, v[24:27]
	v_pk_mul_f32 v[26:27], v[118:119], v[0:1] op_sel_hi:[1,0]
	v_pk_mul_f32 v[24:25], v[116:117], v[0:1] op_sel_hi:[1,0]
	ds_write_b128 v224, v[24:27] offset:1024
	v_pk_mul_f32 v[26:27], v[122:123], v[0:1] op_sel_hi:[1,0]
	v_pk_mul_f32 v[24:25], v[120:121], v[0:1] op_sel_hi:[1,0]
	ds_write_b128 v224, v[24:27] offset:2048
	v_pk_mul_f32 v[26:27], v[126:127], v[0:1] op_sel_hi:[1,0]
	v_pk_mul_f32 v[24:25], v[124:125], v[0:1] op_sel_hi:[1,0]
	global_load_ushort v0, v[130:131], off offset:2566
	ds_write_b128 v224, v[24:27] offset:3072
	s_waitcnt vmcnt(0)
	v_lshlrev_b32_e32 v0, 16, v0
	v_mul_f32_e32 v0, 0xbfb8aa3b, v0
	v_exp_f32_e32 v0, v0
	s_nop 0
	v_add_f32_e32 v0, 1.0, v0
	v_div_scale_f32 v2, s[2:3], v0, v0, 1.0
	v_rcp_f32_e32 v3, v2
	v_readlane_b32 s2, v253, 26
	s_add_u32 s0, s2, s0
	v_readlane_b32 s2, v253, 27
	v_fma_f32 v24, -v2, v3, 1.0
	v_fmac_f32_e32 v3, v24, v3
	v_div_scale_f32 v24, vcc, 1.0, v0, 1.0
	v_mul_f32_e32 v25, v24, v3
	v_fma_f32 v26, -v2, v25, v24
	v_fmac_f32_e32 v25, v26, v3
	v_fma_f32 v2, -v2, v25, v24
	v_div_fmas_f32 v2, v2, v3, v25
	v_div_fixup_f32 v0, v2, v0, 1.0
	v_pk_mul_f32 v[26:27], v[98:99], v[0:1] op_sel_hi:[1,0]
	v_pk_mul_f32 v[24:25], v[96:97], v[0:1] op_sel_hi:[1,0]
	ds_write_b128 v224, v[24:27] offset:4096
	v_pk_mul_f32 v[26:27], v[102:103], v[0:1] op_sel_hi:[1,0]
	v_pk_mul_f32 v[24:25], v[100:101], v[0:1] op_sel_hi:[1,0]
	ds_write_b128 v224, v[24:27] offset:5120
	v_pk_mul_f32 v[26:27], v[106:107], v[0:1] op_sel_hi:[1,0]
	v_pk_mul_f32 v[24:25], v[104:105], v[0:1] op_sel_hi:[1,0]
	ds_write_b128 v224, v[24:27] offset:6144
	v_pk_mul_f32 v[26:27], v[110:111], v[0:1] op_sel_hi:[1,0]
	v_pk_mul_f32 v[24:25], v[108:109], v[0:1] op_sel_hi:[1,0]
	s_addc_u32 s2, s2, 0
	s_lshl_b32 s6, s6, 1
	ds_write_b128 v224, v[24:27] offset:7168
	s_add_u32 s8, s0, s6
	v_mov_b32_e32 v26, v210
	v_mov_b32_e32 v0, v162
	s_addc_u32 s9, s2, 0
	s_lshl_b32 s0, s93, 14
	v_readlane_b32 s2, v253, 30
	s_add_u32 s2, s2, s0
	v_ashrrev_i32_e32 v2, 3, v0
	v_readlane_b32 s0, v253, 31
	v_writelane_b32 v255, s8, 5
	v_ashrrev_i32_e32 v3, 31, v2
	s_addc_u32 s3, s0, 0
	v_lshlrev_b32_e32 v0, 4, v0
	v_writelane_b32 v255, s9, 6
	v_lshlrev_b64 v[24:25], 14, v[2:3]
	v_and_b32_e32 v0, 0x70, v0
	v_writelane_b32 v255, s2, 7
	s_movk_i32 s0, 0x90
	s_cmp_gt_i32 s7, -1
	v_lshl_add_u64 v[24:25], s[2:3], 0, v[24:25]
	v_lshl_add_u64 v[108:109], s[8:9], 0, v[0:1]
	v_lshl_add_u64 v[110:111], v[24:25], 0, v[0:1]
	v_mul_lo_u32 v27, v2, s0
	s_cselect_b64 s[8:9], -1, 0
	v_lshlrev_b64 v[24:25], 8, v[2:3]
	v_writelane_b32 v255, s3, 8
	s_and_b64 vcc, exec, s[8:9]
	v_add3_u32 v3, 0, v27, v0
	v_lshl_add_u64 v[24:25], v[108:109], 0, v[24:25]
	v_max_f32_e32 v0, v228, v228
	v_max_f32_e32 v24, v227, v227
	v_max_f32_e32 v0, v24, v0
	v_mul_f32_e32 v0, v226, v0
	v_mul_f32_e32 v0, 0x3f83d70a, v0
	v_fmamk_f32 v227, v0, 0x3fb8aa3b, v189
	s_add_i32 s36, s7, 1
	s_mov_b32 s37, 0
.Lattn_slc:
	s_mov_b64 exec, -1
	s_waitcnt vmcnt(0) lgkmcnt(0)
	v_lshrrev_b32_e32 v0, 6, v162
	s_nop 0
	v_readfirstlane_b32 s49, v0
	v_readlane_b32 s58, v255, 5
	v_readlane_b32 s59, v255, 6
	v_readlane_b32 s60, v255, 7
	v_readlane_b32 s61, v255, 8
	s_lshl_b32 s40, s49, 10
	s_add_i32 s41, s40, 0x8000
	s_add_i32 s48, s36, -1
	s_mov_b32 s43, 0
	s_mov_b32 s45, 0
	s_mov_b32 s38, 0
	v_xor_b32_e32 v42, 0x80000000, v227
	v_lshrrev_b32_e32 v120, 4, v210
	v_lshrrev_b32_e32 v0, 2, v211
	v_and_b32_e32 v129, 3, v211
	v_lshl_add_u32 v129, v0, 3, v129
	v_bfe_u32 v171, v211, 1, 1
	v_bfe_u32 v174, v211, 2, 1
	v_lshl_or_b32 v171, v174, 1, v171
	v_xor_b32_e32 v171, v120, v171
	v_bfe_u32 v174, v211, 3, 1
	v_lshlrev_b32_e32 v96, 7, v129
	v_lshl_add_u32 v96, v174, 6, v96
	v_lshl_add_u32 v96, v171, 4, v96
	v_xor_b32_e32 v97, 64, v96
	v_bfe_u32 v171, v211, 1, 2
	v_xor_b32_e32 v171, v120, v171
	v_lshlrev_b32_e32 v98, 7, v211
	v_lshl_add_u32 v98, v174, 6, v98
	v_lshl_add_u32 v98, v171, 4, v98
	v_xor_b32_e32 v102, 64, v98
	v_lshrrev_b32_e32 v0, 3, v210
	v_and_b32_e32 v129, 7, v210
	v_bfe_u32 v171, v210, 4, 1
	s_and_b32 s62, s49, 3
	s_lshl_b32 s62, s62, 1
	v_or_b32_e32 v171, s62, v171
	v_xor_b32_e32 v171, v129, v171
	s_lshl_b32 s63, s49, 11
	v_lshl_add_u32 v122, v0, 8, s63
	v_lshl_add_u32 v122, v171, 4, v122
	v_mov_b32_e32 v123, 0
	v_lshl_add_u64 v[106:107], s[58:59], 0, v[122:123]
	v_bfe_u32 v171, v210, 4, 2
	s_and_b32 s62, s49, 1
	s_lshl_b32 s62, s62, 2
	v_or_b32_e32 v171, s62, v171
	v_xor_b32_e32 v171, v129, v171
	s_lshl_b32 s63, s49, 17
	v_lshl_add_u32 v122, v0, 14, s63
	v_lshl_add_u32 v122, v171, 4, v122
	v_lshl_add_u64 v[114:115], s[60:61], 0, v[122:123]
	s_lshl_b32 s62, s48, 6
	v_subrev_u32_e32 v103, s62, v172
	v_lshlrev_b32_e32 v0, 3, v120
	v_sub_u32_e32 v103, v103, v0
	v_mov_b32_e32 v24, 0
	v_mov_b32_e32 v25, 0
	v_mov_b32_e32 v26, 0
	v_mov_b32_e32 v27, 0
	v_mov_b32_e32 v28, 0
	v_mov_b32_e32 v29, 0
	v_mov_b32_e32 v30, 0
	v_mov_b32_e32 v31, 0
	v_mov_b32_e32 v32, 0
	v_mov_b32_e32 v33, 0
	v_mov_b32_e32 v34, 0
	v_mov_b32_e32 v35, 0
	v_mov_b32_e32 v36, 0
	v_mov_b32_e32 v37, 0
	v_mov_b32_e32 v38, 0
	v_mov_b32_e32 v39, 0
	v_mov_b32_e32 v52, 0
	v_mov_b32_e32 v53, 0
	v_mov_b32_e32 v54, 0
	v_mov_b32_e32 v55, 0
	v_mov_b32_e32 v56, 0
	v_mov_b32_e32 v57, 0
	v_mov_b32_e32 v58, 0
	v_mov_b32_e32 v59, 0
	v_mov_b32_e32 v60, 0
	v_mov_b32_e32 v61, 0
	v_mov_b32_e32 v62, 0
	v_mov_b32_e32 v63, 0
	v_mov_b32_e32 v64, 0
	v_mov_b32_e32 v65, 0
	v_mov_b32_e32 v66, 0
	v_mov_b32_e32 v67, 0
	v_mov_b32_e32 v112, 0
	v_mov_b32_e32 v113, 0
	v_mov_b32_e32 v132, 0
	v_mov_b32_e32 v133, 0
	v_mov_b32_e32 v134, 0
	v_mov_b32_e32 v135, 0
	v_mov_b32_e32 v136, 0
	v_mov_b32_e32 v137, 0
	v_mov_b32_e32 v138, 0
	v_mov_b32_e32 v139, 0
	v_mov_b32_e32 v140, 0
	v_mov_b32_e32 v141, 0
	v_mov_b32_e32 v142, 0
	v_mov_b32_e32 v143, 0
	v_mov_b32_e32 v144, 0
	v_mov_b32_e32 v145, 0
	v_mov_b32_e32 v146, 0
	v_mov_b32_e32 v147, 0
	v_mov_b32_e32 v148, 0
	v_mov_b32_e32 v149, 0
	v_mov_b32_e32 v150, 0
	v_mov_b32_e32 v151, 0
	v_mov_b32_e32 v152, 0
	v_mov_b32_e32 v153, 0
	v_mov_b32_e32 v154, 0
	v_mov_b32_e32 v155, 0
	v_mov_b32_e32 v176, 0
	v_mov_b32_e32 v177, 0
	v_mov_b32_e32 v178, 0
	v_mov_b32_e32 v179, 0
	v_mov_b32_e32 v180, 0
	v_mov_b32_e32 v181, 0
	v_mov_b32_e32 v182, 0
	v_mov_b32_e32 v183, 0
	v_mov_b32_e32 v198, v20
	v_mov_b32_e32 v199, v21
	v_and_b32_e32 v160, 1, v20
	v_cmp_eq_u32_e64 s[50:51], 1, v160
	s_nop 1
	v_cndmask_b32_e64 v204, v197, v42, s[50:51]
	v_mov_b32_e32 v205, v204
	v_mov_b32_e32 v206, v204
	v_mov_b32_e32 v207, v204
	s_min_u32 s46, s48, 0
	s_lshl_b32 s42, s46, 14
	v_lshl_add_u64 v[40:41], s[42:43], 0, v[106:107]
	s_add_i32 m0, s40, 0x0
	s_nop 0
	global_load_lds_dwordx4 v[40:41], off
	s_min_u32 s46, s48, 1
	s_lshl_b32 s42, s46, 14
	v_lshl_add_u64 v[40:41], s[42:43], 0, v[106:107]
	s_add_i32 m0, s40, 0x2000
	s_nop 0
	global_load_lds_dwordx4 v[40:41], off
	s_min_u32 s47, s48, 0
	s_lshl_b32 s44, s47, 7
	v_lshl_add_u64 v[122:123], s[44:45], 0, v[114:115]
	s_add_i32 m0, s41, 0x6000
	s_nop 0
	global_load_lds_dwordx4 v[122:123], off
	s_min_u32 s46, s48, 2
	s_lshl_b32 s42, s46, 14
	v_lshl_add_u64 v[40:41], s[42:43], 0, v[106:107]
	s_add_i32 m0, s40, 0x4000
	s_nop 0
	global_load_lds_dwordx4 v[40:41], off
	s_min_u32 s47, s48, 0
	s_lshl_b32 s44, s47, 7
	v_lshl_add_u64 v[122:123], s[44:45], 0, v[114:115]
	s_add_i32 m0, s41, 0x0
	s_nop 0
	global_load_lds_dwordx4 v[122:123], off
	s_min_u32 s46, s48, 3
	s_lshl_b32 s42, s46, 14
	v_lshl_add_u64 v[40:41], s[42:43], 0, v[106:107]
	s_add_i32 m0, s40, 0x6000
	s_nop 0
	global_load_lds_dwordx4 v[40:41], off
	s_min_u32 s47, s48, 1
	s_lshl_b32 s44, s47, 7
	v_lshl_add_u64 v[122:123], s[44:45], 0, v[114:115]
	s_add_i32 m0, s41, 0x2000
	s_nop 0
	global_load_lds_dwordx4 v[122:123], off
	s_waitcnt vmcnt(6)
	s_barrier
	ds_read_b128 v[240:243], v96 offset:0
	ds_read_b128 v[244:247], v97 offset:0
	ds_read_b128 v[248:251], v96 offset:512
	ds_read_b128 v[116:119], v97 offset:512
	ds_read_b128 v[124:127], v96 offset:4096
	ds_read_b128 v[156:159], v97 offset:4096
	ds_read_b128 v[188:191], v96 offset:4608
	ds_read_b128 v[200:203], v97 offset:4608
.Lattn_it0:
	s_waitcnt vmcnt(4) lgkmcnt(0)
	s_barrier
	s_add_i32 s46, s38, 4
	s_min_u32 s46, s46, s48
	s_lshl_b32 s42, s46, 14
	s_add_i32 s47, s38, 2
	s_min_u32 s47, s47, s48
	s_lshl_b32 s44, s47, 7
	v_lshl_add_u64 v[40:41], s[42:43], 0, v[106:107]
	v_lshl_add_u64 v[122:123], s[44:45], 0, v[114:115]
	v_mfma_f32_16x16x32_bf16 v[68:71], v[240:243], v[4:7], v[204:207]
	v_cvt_pk_bf16_f32 v184, v132, v133
	v_add_f32_e32 v112, v112, v132
	v_add_f32_e32 v113, v113, v148
	v_mfma_f32_16x16x32_bf16 v[84:87], v[240:243], v[12:15], v[204:207]
	v_cvt_pk_bf16_f32 v185, v134, v135
	v_add_f32_e32 v112, v112, v133
	v_add_f32_e32 v113, v113, v149
	ds_read_b128 v[240:243], v98 offset:57344
	s_add_i32 m0, s40, 0x0
	s_nop 0
	global_load_lds_dwordx4 v[40:41], off
	v_mfma_f32_16x16x32_bf16 v[68:71], v[244:247], v[8:11], v[68:71]
	v_cvt_pk_bf16_f32 v186, v136, v137
	v_add_f32_e32 v112, v112, v134
	v_add_f32_e32 v113, v113, v150
	v_mfma_f32_16x16x32_bf16 v[84:87], v[244:247], v[16:19], v[84:87]
	v_cvt_pk_bf16_f32 v187, v138, v139
	v_add_f32_e32 v112, v112, v135
	v_add_f32_e32 v113, v113, v151
	ds_read_b128 v[244:247], v102 offset:57344
	s_add_i32 m0, s41, 0x4000
	s_nop 0
	global_load_lds_dwordx4 v[122:123], off
	v_mfma_f32_16x16x32_bf16 v[72:75], v[248:251], v[4:7], v[204:207]
	v_cvt_pk_bf16_f32 v228, v140, v141
	v_add_f32_e32 v112, v112, v136
	v_add_f32_e32 v113, v113, v152
	v_mfma_f32_16x16x32_bf16 v[88:91], v[248:251], v[12:15], v[204:207]
	v_cvt_pk_bf16_f32 v229, v142, v143
	v_add_f32_e32 v112, v112, v137
	v_add_f32_e32 v113, v113, v153
	ds_read_b128 v[248:251], v98 offset:59392
	v_mfma_f32_16x16x32_bf16 v[72:75], v[116:119], v[8:11], v[72:75]
	v_cvt_pk_bf16_f32 v230, v144, v145
	v_add_f32_e32 v112, v112, v138
	v_add_f32_e32 v113, v113, v154
	v_mfma_f32_16x16x32_bf16 v[88:91], v[116:119], v[16:19], v[88:91]
	v_cvt_pk_bf16_f32 v231, v146, v147
	v_add_f32_e32 v112, v112, v139
	v_add_f32_e32 v113, v113, v155
	ds_read_b128 v[116:119], v102 offset:59392
	v_mfma_f32_16x16x32_bf16 v[76:79], v[124:127], v[4:7], v[204:207]
	v_cvt_pk_bf16_f32 v232, v148, v149
	v_add_f32_e32 v112, v112, v140
	v_add_f32_e32 v113, v113, v176
	v_mfma_f32_16x16x32_bf16 v[92:95], v[124:127], v[12:15], v[204:207]
	v_cvt_pk_bf16_f32 v233, v150, v151
	v_add_f32_e32 v112, v112, v141
	v_add_f32_e32 v113, v113, v177
	ds_read_b128 v[124:127], v98 offset:61440
	v_mfma_f32_16x16x32_bf16 v[76:79], v[156:159], v[8:11], v[76:79]
	v_cvt_pk_bf16_f32 v234, v152, v153
	v_add_f32_e32 v112, v112, v142
	v_add_f32_e32 v113, v113, v178
	v_mfma_f32_16x16x32_bf16 v[92:95], v[156:159], v[16:19], v[92:95]
	v_cvt_pk_bf16_f32 v235, v154, v155
	v_add_f32_e32 v112, v112, v143
	v_add_f32_e32 v113, v113, v179
	ds_read_b128 v[156:159], v102 offset:61440
	v_mfma_f32_16x16x32_bf16 v[80:83], v[188:191], v[4:7], v[204:207]
	v_cvt_pk_bf16_f32 v236, v176, v177
	v_add_f32_e32 v112, v112, v144
	v_add_f32_e32 v113, v113, v180
	v_mfma_f32_16x16x32_bf16 v[108:111], v[188:191], v[12:15], v[204:207]
	v_cvt_pk_bf16_f32 v237, v178, v179
	v_add_f32_e32 v112, v112, v145
	v_add_f32_e32 v113, v113, v181
	ds_read_b128 v[188:191], v98 offset:63488
	v_mfma_f32_16x16x32_bf16 v[80:83], v[200:203], v[8:11], v[80:83]
	v_cvt_pk_bf16_f32 v238, v180, v181
	v_add_f32_e32 v112, v112, v146
	v_add_f32_e32 v113, v113, v182
	v_mfma_f32_16x16x32_bf16 v[108:111], v[200:203], v[16:19], v[108:111]
	v_cvt_pk_bf16_f32 v239, v182, v183
	v_add_f32_e32 v112, v112, v147
	v_add_f32_e32 v113, v113, v183
	ds_read_b128 v[200:203], v102 offset:63488
	s_waitcnt lgkmcnt(7)
	v_mfma_f32_16x16x32_bf16 v[64:67], v[240:243], v[184:187], v[64:67]
	v_exp_f32_e32 v68, v68
	v_exp_f32_e32 v69, v69
	v_mfma_f32_16x16x32_bf16 v[36:39], v[240:243], v[232:235], v[36:39]
	v_exp_f32_e32 v70, v70
	v_exp_f32_e32 v71, v71
	ds_read_b128 v[240:243], v96 offset:8192
	s_waitcnt lgkmcnt(7)
	v_mfma_f32_16x16x32_bf16 v[64:67], v[244:247], v[228:231], v[64:67]
	v_exp_f32_e32 v84, v84
	v_exp_f32_e32 v85, v85
	v_mfma_f32_16x16x32_bf16 v[36:39], v[244:247], v[236:239], v[36:39]
	v_exp_f32_e32 v86, v86
	v_exp_f32_e32 v87, v87
	ds_read_b128 v[244:247], v97 offset:8192
	s_waitcnt lgkmcnt(7)
	v_mfma_f32_16x16x32_bf16 v[56:59], v[248:251], v[184:187], v[56:59]
	v_exp_f32_e32 v72, v72
	v_exp_f32_e32 v73, v73
	v_mfma_f32_16x16x32_bf16 v[32:35], v[248:251], v[232:235], v[32:35]
	v_exp_f32_e32 v74, v74
	v_exp_f32_e32 v75, v75
	ds_read_b128 v[248:251], v96 offset:8704
	s_waitcnt lgkmcnt(7)
	v_mfma_f32_16x16x32_bf16 v[56:59], v[116:119], v[228:231], v[56:59]
	v_exp_f32_e32 v88, v88
	v_exp_f32_e32 v89, v89
	v_mfma_f32_16x16x32_bf16 v[32:35], v[116:119], v[236:239], v[32:35]
	v_exp_f32_e32 v90, v90
	v_exp_f32_e32 v91, v91
	ds_read_b128 v[116:119], v97 offset:8704
	s_waitcnt lgkmcnt(7)
	v_mfma_f32_16x16x32_bf16 v[52:55], v[124:127], v[184:187], v[52:55]
	v_exp_f32_e32 v76, v76
	v_exp_f32_e32 v77, v77
	v_mfma_f32_16x16x32_bf16 v[24:27], v[124:127], v[232:235], v[24:27]
	v_exp_f32_e32 v78, v78
	v_exp_f32_e32 v79, v79
	ds_read_b128 v[124:127], v96 offset:12288
	s_waitcnt lgkmcnt(7)
	v_mfma_f32_16x16x32_bf16 v[52:55], v[156:159], v[228:231], v[52:55]
	v_exp_f32_e32 v92, v92
	v_exp_f32_e32 v93, v93
	v_mfma_f32_16x16x32_bf16 v[24:27], v[156:159], v[236:239], v[24:27]
	v_exp_f32_e32 v94, v94
	v_exp_f32_e32 v95, v95
	ds_read_b128 v[156:159], v97 offset:12288
	s_waitcnt lgkmcnt(7)
	v_mfma_f32_16x16x32_bf16 v[60:63], v[188:191], v[184:187], v[60:63]
	v_exp_f32_e32 v80, v80
	v_exp_f32_e32 v81, v81
	v_mfma_f32_16x16x32_bf16 v[28:31], v[188:191], v[232:235], v[28:31]
	v_exp_f32_e32 v82, v82
	v_exp_f32_e32 v83, v83
	ds_read_b128 v[188:191], v96 offset:12800
	s_waitcnt lgkmcnt(7)
	v_mfma_f32_16x16x32_bf16 v[60:63], v[200:203], v[228:231], v[60:63]
	v_exp_f32_e32 v108, v108
	v_exp_f32_e32 v109, v109
	v_mfma_f32_16x16x32_bf16 v[28:31], v[200:203], v[236:239], v[28:31]
	v_exp_f32_e32 v110, v110
	v_exp_f32_e32 v111, v111
	ds_read_b128 v[200:203], v97 offset:12800
	s_cmp_eq_u32 s38, s48
	s_cbranch_scc0 .Lattn_nofix0
	v_cmp_le_i32_e64 s[50:51], 0, v103
	v_cmp_le_i32_e64 s[52:53], 1, v103
	v_cmp_le_i32_e64 s[56:57], 2, v103
	v_cndmask_b32_e64 v68, 0, v68, s[50:51]
	v_cndmask_b32_e64 v84, 0, v84, s[50:51]
	v_cmp_le_i32_e64 s[50:51], 3, v103
	v_cndmask_b32_e64 v69, 0, v69, s[52:53]
	v_cndmask_b32_e64 v85, 0, v85, s[52:53]
	v_cmp_le_i32_e64 s[52:53], 4, v103
	v_cndmask_b32_e64 v70, 0, v70, s[56:57]
	v_cndmask_b32_e64 v86, 0, v86, s[56:57]
	v_cmp_le_i32_e64 s[56:57], 5, v103
	v_cndmask_b32_e64 v71, 0, v71, s[50:51]
	v_cndmask_b32_e64 v87, 0, v87, s[50:51]
	v_cmp_le_i32_e64 s[50:51], 6, v103
	v_cndmask_b32_e64 v72, 0, v72, s[52:53]
	v_cndmask_b32_e64 v88, 0, v88, s[52:53]
	v_cmp_le_i32_e64 s[52:53], 7, v103
	v_cndmask_b32_e64 v73, 0, v73, s[56:57]
	v_cndmask_b32_e64 v89, 0, v89, s[56:57]
	v_cmp_le_i32_e64 s[56:57], 32, v103
	v_cndmask_b32_e64 v74, 0, v74, s[50:51]
	v_cndmask_b32_e64 v90, 0, v90, s[50:51]
	v_cmp_le_i32_e64 s[50:51], 33, v103
	v_cndmask_b32_e64 v75, 0, v75, s[52:53]
	v_cndmask_b32_e64 v91, 0, v91, s[52:53]
	v_cmp_le_i32_e64 s[52:53], 34, v103
	v_cndmask_b32_e64 v76, 0, v76, s[56:57]
	v_cndmask_b32_e64 v92, 0, v92, s[56:57]
	v_cmp_le_i32_e64 s[56:57], 35, v103
	v_cndmask_b32_e64 v77, 0, v77, s[50:51]
	v_cndmask_b32_e64 v93, 0, v93, s[50:51]
	v_cmp_le_i32_e64 s[50:51], 36, v103
	v_cndmask_b32_e64 v78, 0, v78, s[52:53]
	v_cndmask_b32_e64 v94, 0, v94, s[52:53]
	v_cmp_le_i32_e64 s[52:53], 37, v103
	v_cndmask_b32_e64 v79, 0, v79, s[56:57]
	v_cndmask_b32_e64 v95, 0, v95, s[56:57]
	v_cmp_le_i32_e64 s[56:57], 38, v103
	v_cndmask_b32_e64 v80, 0, v80, s[50:51]
	v_cndmask_b32_e64 v108, 0, v108, s[50:51]
	v_cmp_le_i32_e64 s[50:51], 39, v103
	v_cndmask_b32_e64 v81, 0, v81, s[52:53]
	v_cndmask_b32_e64 v109, 0, v109, s[52:53]
	v_cndmask_b32_e64 v82, 0, v82, s[56:57]
	v_cndmask_b32_e64 v110, 0, v110, s[56:57]
	v_cndmask_b32_e64 v83, 0, v83, s[50:51]
	v_cndmask_b32_e64 v111, 0, v111, s[50:51]
.Lattn_nofix0:
	s_cmp_eq_u32 s38, s36
	s_cbranch_scc1 .Lattn_done
	s_add_i32 s38, s38, 1
	s_cmp_eq_u32 s38, 64
	s_cbranch_scc0 .Lattn_nosw0
	v_mov_b32_e32 v198, v22
	v_mov_b32_e32 v199, v23
.Lattn_nosw0:
	v_lshrrev_b64 v[160:161], s38, v[198:199]
	v_and_b32_e32 v160, 1, v160
	v_cmp_eq_u32_e64 s[50:51], 1, v160
	s_nop 1
	v_cndmask_b32_e64 v204, v197, v42, s[50:51]
	v_mov_b32_e32 v205, v204
	v_mov_b32_e32 v206, v204
	v_mov_b32_e32 v207, v204
.Lattn_it1:
	s_waitcnt vmcnt(4) lgkmcnt(0)
	s_barrier
	s_add_i32 s46, s38, 4
	s_min_u32 s46, s46, s48
	s_lshl_b32 s42, s46, 14
	s_add_i32 s47, s38, 2
	s_min_u32 s47, s47, s48
	s_lshl_b32 s44, s47, 7
	v_lshl_add_u64 v[40:41], s[42:43], 0, v[106:107]
	v_lshl_add_u64 v[122:123], s[44:45], 0, v[114:115]
	v_mfma_f32_16x16x32_bf16 v[132:135], v[240:243], v[4:7], v[204:207]
	v_cvt_pk_bf16_f32 v184, v68, v69
	v_add_f32_e32 v112, v112, v68
	v_add_f32_e32 v113, v113, v84
	v_mfma_f32_16x16x32_bf16 v[148:151], v[240:243], v[12:15], v[204:207]
	v_cvt_pk_bf16_f32 v185, v70, v71
	v_add_f32_e32 v112, v112, v69
	v_add_f32_e32 v113, v113, v85
	ds_read_b128 v[240:243], v98 offset:32768
	s_add_i32 m0, s40, 0x2000
	s_nop 0
	global_load_lds_dwordx4 v[40:41], off
	v_mfma_f32_16x16x32_bf16 v[132:135], v[244:247], v[8:11], v[132:135]
	v_cvt_pk_bf16_f32 v186, v72, v73
	v_add_f32_e32 v112, v112, v70
	v_add_f32_e32 v113, v113, v86
	v_mfma_f32_16x16x32_bf16 v[148:151], v[244:247], v[16:19], v[148:151]
	v_cvt_pk_bf16_f32 v187, v74, v75
	v_add_f32_e32 v112, v112, v71
	v_add_f32_e32 v113, v113, v87
	ds_read_b128 v[244:247], v102 offset:32768
	s_add_i32 m0, s41, 0x6000
	s_nop 0
	global_load_lds_dwordx4 v[122:123], off
	v_mfma_f32_16x16x32_bf16 v[136:139], v[248:251], v[4:7], v[204:207]
	v_cvt_pk_bf16_f32 v228, v76, v77
	v_add_f32_e32 v112, v112, v72
	v_add_f32_e32 v113, v113, v88
	v_mfma_f32_16x16x32_bf16 v[152:155], v[248:251], v[12:15], v[204:207]
	v_cvt_pk_bf16_f32 v229, v78, v79
	v_add_f32_e32 v112, v112, v73
	v_add_f32_e32 v113, v113, v89
	ds_read_b128 v[248:251], v98 offset:34816
	v_mfma_f32_16x16x32_bf16 v[136:139], v[116:119], v[8:11], v[136:139]
	v_cvt_pk_bf16_f32 v230, v80, v81
	v_add_f32_e32 v112, v112, v74
	v_add_f32_e32 v113, v113, v90
	v_mfma_f32_16x16x32_bf16 v[152:155], v[116:119], v[16:19], v[152:155]
	v_cvt_pk_bf16_f32 v231, v82, v83
	v_add_f32_e32 v112, v112, v75
	v_add_f32_e32 v113, v113, v91
	ds_read_b128 v[116:119], v102 offset:34816
	v_mfma_f32_16x16x32_bf16 v[140:143], v[124:127], v[4:7], v[204:207]
	v_cvt_pk_bf16_f32 v232, v84, v85
	v_add_f32_e32 v112, v112, v76
	v_add_f32_e32 v113, v113, v92
	v_mfma_f32_16x16x32_bf16 v[176:179], v[124:127], v[12:15], v[204:207]
	v_cvt_pk_bf16_f32 v233, v86, v87
	v_add_f32_e32 v112, v112, v77
	v_add_f32_e32 v113, v113, v93
	ds_read_b128 v[124:127], v98 offset:36864
	v_mfma_f32_16x16x32_bf16 v[140:143], v[156:159], v[8:11], v[140:143]
	v_cvt_pk_bf16_f32 v234, v88, v89
	v_add_f32_e32 v112, v112, v78
	v_add_f32_e32 v113, v113, v94
	v_mfma_f32_16x16x32_bf16 v[176:179], v[156:159], v[16:19], v[176:179]
	v_cvt_pk_bf16_f32 v235, v90, v91
	v_add_f32_e32 v112, v112, v79
	v_add_f32_e32 v113, v113, v95
	ds_read_b128 v[156:159], v102 offset:36864
	v_mfma_f32_16x16x32_bf16 v[144:147], v[188:191], v[4:7], v[204:207]
	v_cvt_pk_bf16_f32 v236, v92, v93
	v_add_f32_e32 v112, v112, v80
	v_add_f32_e32 v113, v113, v108
	v_mfma_f32_16x16x32_bf16 v[180:183], v[188:191], v[12:15], v[204:207]
	v_cvt_pk_bf16_f32 v237, v94, v95
	v_add_f32_e32 v112, v112, v81
	v_add_f32_e32 v113, v113, v109
	ds_read_b128 v[188:191], v98 offset:38912
	v_mfma_f32_16x16x32_bf16 v[144:147], v[200:203], v[8:11], v[144:147]
	v_cvt_pk_bf16_f32 v238, v108, v109
	v_add_f32_e32 v112, v112, v82
	v_add_f32_e32 v113, v113, v110
	v_mfma_f32_16x16x32_bf16 v[180:183], v[200:203], v[16:19], v[180:183]
	v_cvt_pk_bf16_f32 v239, v110, v111
	v_add_f32_e32 v112, v112, v83
	v_add_f32_e32 v113, v113, v111
	ds_read_b128 v[200:203], v102 offset:38912
	s_waitcnt lgkmcnt(7)
	v_mfma_f32_16x16x32_bf16 v[64:67], v[240:243], v[184:187], v[64:67]
	v_exp_f32_e32 v132, v132
	v_exp_f32_e32 v133, v133
	v_mfma_f32_16x16x32_bf16 v[36:39], v[240:243], v[232:235], v[36:39]
	v_exp_f32_e32 v134, v134
	v_exp_f32_e32 v135, v135
	ds_read_b128 v[240:243], v96 offset:16384
	s_waitcnt lgkmcnt(7)
	v_mfma_f32_16x16x32_bf16 v[64:67], v[244:247], v[228:231], v[64:67]
	v_exp_f32_e32 v148, v148
	v_exp_f32_e32 v149, v149
	v_mfma_f32_16x16x32_bf16 v[36:39], v[244:247], v[236:239], v[36:39]
	v_exp_f32_e32 v150, v150
	v_exp_f32_e32 v151, v151
	ds_read_b128 v[244:247], v97 offset:16384
	s_waitcnt lgkmcnt(7)
	v_mfma_f32_16x16x32_bf16 v[56:59], v[248:251], v[184:187], v[56:59]
	v_exp_f32_e32 v136, v136
	v_exp_f32_e32 v137, v137
	v_mfma_f32_16x16x32_bf16 v[32:35], v[248:251], v[232:235], v[32:35]
	v_exp_f32_e32 v138, v138
	v_exp_f32_e32 v139, v139
	ds_read_b128 v[248:251], v96 offset:16896
	s_waitcnt lgkmcnt(7)
	v_mfma_f32_16x16x32_bf16 v[56:59], v[116:119], v[228:231], v[56:59]
	v_exp_f32_e32 v152, v152
	v_exp_f32_e32 v153, v153
	v_mfma_f32_16x16x32_bf16 v[32:35], v[116:119], v[236:239], v[32:35]
	v_exp_f32_e32 v154, v154
	v_exp_f32_e32 v155, v155
	ds_read_b128 v[116:119], v97 offset:16896
	s_waitcnt lgkmcnt(7)
	v_mfma_f32_16x16x32_bf16 v[52:55], v[124:127], v[184:187], v[52:55]
	v_exp_f32_e32 v140, v140
	v_exp_f32_e32 v141, v141
	v_mfma_f32_16x16x32_bf16 v[24:27], v[124:127], v[232:235], v[24:27]
	v_exp_f32_e32 v142, v142
	v_exp_f32_e32 v143, v143
	ds_read_b128 v[124:127], v96 offset:20480
	s_waitcnt lgkmcnt(7)
	v_mfma_f32_16x16x32_bf16 v[52:55], v[156:159], v[228:231], v[52:55]
	v_exp_f32_e32 v176, v176
	v_exp_f32_e32 v177, v177
	v_mfma_f32_16x16x32_bf16 v[24:27], v[156:159], v[236:239], v[24:27]
	v_exp_f32_e32 v178, v178
	v_exp_f32_e32 v179, v179
	ds_read_b128 v[156:159], v97 offset:20480
	s_waitcnt lgkmcnt(7)
	v_mfma_f32_16x16x32_bf16 v[60:63], v[188:191], v[184:187], v[60:63]
	v_exp_f32_e32 v144, v144
	v_exp_f32_e32 v145, v145
	v_mfma_f32_16x16x32_bf16 v[28:31], v[188:191], v[232:235], v[28:31]
	v_exp_f32_e32 v146, v146
	v_exp_f32_e32 v147, v147
	ds_read_b128 v[188:191], v96 offset:20992
	s_waitcnt lgkmcnt(7)
	v_mfma_f32_16x16x32_bf16 v[60:63], v[200:203], v[228:231], v[60:63]
	v_exp_f32_e32 v180, v180
	v_exp_f32_e32 v181, v181
	v_mfma_f32_16x16x32_bf16 v[28:31], v[200:203], v[236:239], v[28:31]
	v_exp_f32_e32 v182, v182
	v_exp_f32_e32 v183, v183
	ds_read_b128 v[200:203], v97 offset:20992
	s_cmp_eq_u32 s38, s48
	s_cbranch_scc0 .Lattn_nofix1
	v_cmp_le_i32_e64 s[50:51], 0, v103
	v_cmp_le_i32_e64 s[52:53], 1, v103
	v_cmp_le_i32_e64 s[56:57], 2, v103
	v_cndmask_b32_e64 v132, 0, v132, s[50:51]
	v_cndmask_b32_e64 v148, 0, v148, s[50:51]
	v_cmp_le_i32_e64 s[50:51], 3, v103
	v_cndmask_b32_e64 v133, 0, v133, s[52:53]
	v_cndmask_b32_e64 v149, 0, v149, s[52:53]
	v_cmp_le_i32_e64 s[52:53], 4, v103
	v_cndmask_b32_e64 v134, 0, v134, s[56:57]
	v_cndmask_b32_e64 v150, 0, v150, s[56:57]
	v_cmp_le_i32_e64 s[56:57], 5, v103
	v_cndmask_b32_e64 v135, 0, v135, s[50:51]
	v_cndmask_b32_e64 v151, 0, v151, s[50:51]
	v_cmp_le_i32_e64 s[50:51], 6, v103
	v_cndmask_b32_e64 v136, 0, v136, s[52:53]
	v_cndmask_b32_e64 v152, 0, v152, s[52:53]
	v_cmp_le_i32_e64 s[52:53], 7, v103
	v_cndmask_b32_e64 v137, 0, v137, s[56:57]
	v_cndmask_b32_e64 v153, 0, v153, s[56:57]
	v_cmp_le_i32_e64 s[56:57], 32, v103
	v_cndmask_b32_e64 v138, 0, v138, s[50:51]
	v_cndmask_b32_e64 v154, 0, v154, s[50:51]
	v_cmp_le_i32_e64 s[50:51], 33, v103
	v_cndmask_b32_e64 v139, 0, v139, s[52:53]
	v_cndmask_b32_e64 v155, 0, v155, s[52:53]
	v_cmp_le_i32_e64 s[52:53], 34, v103
	v_cndmask_b32_e64 v140, 0, v140, s[56:57]
	v_cndmask_b32_e64 v176, 0, v176, s[56:57]
	v_cmp_le_i32_e64 s[56:57], 35, v103
	v_cndmask_b32_e64 v141, 0, v141, s[50:51]
	v_cndmask_b32_e64 v177, 0, v177, s[50:51]
	v_cmp_le_i32_e64 s[50:51], 36, v103
	v_cndmask_b32_e64 v142, 0, v142, s[52:53]
	v_cndmask_b32_e64 v178, 0, v178, s[52:53]
	v_cmp_le_i32_e64 s[52:53], 37, v103
	v_cndmask_b32_e64 v143, 0, v143, s[56:57]
	v_cndmask_b32_e64 v179, 0, v179, s[56:57]
	v_cmp_le_i32_e64 s[56:57], 38, v103
	v_cndmask_b32_e64 v144, 0, v144, s[50:51]
	v_cndmask_b32_e64 v180, 0, v180, s[50:51]
	v_cmp_le_i32_e64 s[50:51], 39, v103
	v_cndmask_b32_e64 v145, 0, v145, s[52:53]
	v_cndmask_b32_e64 v181, 0, v181, s[52:53]
	v_cndmask_b32_e64 v146, 0, v146, s[56:57]
	v_cndmask_b32_e64 v182, 0, v182, s[56:57]
	v_cndmask_b32_e64 v147, 0, v147, s[50:51]
	v_cndmask_b32_e64 v183, 0, v183, s[50:51]

.Lattn_it2:
	s_waitcnt vmcnt(4) lgkmcnt(0)
	s_barrier
	s_add_i32 s46, s38, 4
	s_min_u32 s46, s46, s48
	s_lshl_b32 s42, s46, 14
	s_add_i32 s47, s38, 2
	s_min_u32 s47, s47, s48
	s_lshl_b32 s44, s47, 7
	v_lshl_add_u64 v[40:41], s[42:43], 0, v[106:107]
	v_lshl_add_u64 v[122:123], s[44:45], 0, v[114:115]
	v_mfma_f32_16x16x32_bf16 v[68:71], v[240:243], v[4:7], v[204:207]
	v_cvt_pk_bf16_f32 v184, v132, v133
	v_add_f32_e32 v112, v112, v132
	v_add_f32_e32 v113, v113, v148
	v_mfma_f32_16x16x32_bf16 v[84:87], v[240:243], v[12:15], v[204:207]
	v_cvt_pk_bf16_f32 v185, v134, v135
	v_add_f32_e32 v112, v112, v133
	v_add_f32_e32 v113, v113, v149
	ds_read_b128 v[240:243], v98 offset:40960
	s_add_i32 m0, s40, 0x4000
	s_nop 0
	global_load_lds_dwordx4 v[40:41], off
	v_mfma_f32_16x16x32_bf16 v[68:71], v[244:247], v[8:11], v[68:71]
	v_cvt_pk_bf16_f32 v186, v136, v137
	v_add_f32_e32 v112, v112, v134
	v_add_f32_e32 v113, v113, v150
	v_mfma_f32_16x16x32_bf16 v[84:87], v[244:247], v[16:19], v[84:87]
	v_cvt_pk_bf16_f32 v187, v138, v139
	v_add_f32_e32 v112, v112, v135
	v_add_f32_e32 v113, v113, v151
	ds_read_b128 v[244:247], v102 offset:40960
	s_add_i32 m0, s41, 0x0
	s_nop 0
	global_load_lds_dwordx4 v[122:123], off
	v_mfma_f32_16x16x32_bf16 v[72:75], v[248:251], v[4:7], v[204:207]
	v_cvt_pk_bf16_f32 v228, v140, v141
	v_add_f32_e32 v112, v112, v136
	v_add_f32_e32 v113, v113, v152
	v_mfma_f32_16x16x32_bf16 v[88:91], v[248:251], v[12:15], v[204:207]
	v_cvt_pk_bf16_f32 v229, v142, v143
	v_add_f32_e32 v112, v112, v137
	v_add_f32_e32 v113, v113, v153
	ds_read_b128 v[248:251], v98 offset:43008
	v_mfma_f32_16x16x32_bf16 v[72:75], v[116:119], v[8:11], v[72:75]
	v_cvt_pk_bf16_f32 v230, v144, v145
	v_add_f32_e32 v112, v112, v138
	v_add_f32_e32 v113, v113, v154
	v_mfma_f32_16x16x32_bf16 v[88:91], v[116:119], v[16:19], v[88:91]
	v_cvt_pk_bf16_f32 v231, v146, v147
	v_add_f32_e32 v112, v112, v139
	v_add_f32_e32 v113, v113, v155
	ds_read_b128 v[116:119], v102 offset:43008
	v_mfma_f32_16x16x32_bf16 v[76:79], v[124:127], v[4:7], v[204:207]
	v_cvt_pk_bf16_f32 v232, v148, v149
	v_add_f32_e32 v112, v112, v140
	v_add_f32_e32 v113, v113, v176
	v_mfma_f32_16x16x32_bf16 v[92:95], v[124:127], v[12:15], v[204:207]
	v_cvt_pk_bf16_f32 v233, v150, v151
	v_add_f32_e32 v112, v112, v141
	v_add_f32_e32 v113, v113, v177
	ds_read_b128 v[124:127], v98 offset:45056
	v_mfma_f32_16x16x32_bf16 v[76:79], v[156:159], v[8:11], v[76:79]
	v_cvt_pk_bf16_f32 v234, v152, v153
	v_add_f32_e32 v112, v112, v142
	v_add_f32_e32 v113, v113, v178
	v_mfma_f32_16x16x32_bf16 v[92:95], v[156:159], v[16:19], v[92:95]
	v_cvt_pk_bf16_f32 v235, v154, v155
	v_add_f32_e32 v112, v112, v143
	v_add_f32_e32 v113, v113, v179
	ds_read_b128 v[156:159], v102 offset:45056
	v_mfma_f32_16x16x32_bf16 v[80:83], v[188:191], v[4:7], v[204:207]
	v_cvt_pk_bf16_f32 v236, v176, v177
	v_add_f32_e32 v112, v112, v144
	v_add_f32_e32 v113, v113, v180
	v_mfma_f32_16x16x32_bf16 v[108:111], v[188:191], v[12:15], v[204:207]
	v_cvt_pk_bf16_f32 v237, v178, v179
	v_add_f32_e32 v112, v112, v145
	v_add_f32_e32 v113, v113, v181
	ds_read_b128 v[188:191], v98 offset:47104
	v_mfma_f32_16x16x32_bf16 v[80:83], v[200:203], v[8:11], v[80:83]
	v_cvt_pk_bf16_f32 v238, v180, v181
	v_add_f32_e32 v112, v112, v146
	v_add_f32_e32 v113, v113, v182
	v_mfma_f32_16x16x32_bf16 v[108:111], v[200:203], v[16:19], v[108:111]
	v_cvt_pk_bf16_f32 v239, v182, v183
	v_add_f32_e32 v112, v112, v147
	v_add_f32_e32 v113, v113, v183
	ds_read_b128 v[200:203], v102 offset:47104
	s_waitcnt lgkmcnt(7)
	v_mfma_f32_16x16x32_bf16 v[64:67], v[240:243], v[184:187], v[64:67]
	v_exp_f32_e32 v68, v68
	v_exp_f32_e32 v69, v69
	v_mfma_f32_16x16x32_bf16 v[36:39], v[240:243], v[232:235], v[36:39]
	v_exp_f32_e32 v70, v70
	v_exp_f32_e32 v71, v71
	ds_read_b128 v[240:243], v96 offset:24576
	s_waitcnt lgkmcnt(7)
	v_mfma_f32_16x16x32_bf16 v[64:67], v[244:247], v[228:231], v[64:67]
	v_exp_f32_e32 v84, v84
	v_exp_f32_e32 v85, v85
	v_mfma_f32_16x16x32_bf16 v[36:39], v[244:247], v[236:239], v[36:39]
	v_exp_f32_e32 v86, v86
	v_exp_f32_e32 v87, v87
	ds_read_b128 v[244:247], v97 offset:24576
	s_waitcnt lgkmcnt(7)
	v_mfma_f32_16x16x32_bf16 v[56:59], v[248:251], v[184:187], v[56:59]
	v_exp_f32_e32 v72, v72
	v_exp_f32_e32 v73, v73
	v_mfma_f32_16x16x32_bf16 v[32:35], v[248:251], v[232:235], v[32:35]
	v_exp_f32_e32 v74, v74
	v_exp_f32_e32 v75, v75
	ds_read_b128 v[248:251], v96 offset:25088
	s_waitcnt lgkmcnt(7)
	v_mfma_f32_16x16x32_bf16 v[56:59], v[116:119], v[228:231], v[56:59]
	v_exp_f32_e32 v88, v88
	v_exp_f32_e32 v89, v89
	v_mfma_f32_16x16x32_bf16 v[32:35], v[116:119], v[236:239], v[32:35]
	v_exp_f32_e32 v90, v90
	v_exp_f32_e32 v91, v91
	ds_read_b128 v[116:119], v97 offset:25088
	s_waitcnt lgkmcnt(7)
	v_mfma_f32_16x16x32_bf16 v[52:55], v[124:127], v[184:187], v[52:55]
	v_exp_f32_e32 v76, v76
	v_exp_f32_e32 v77, v77
	v_mfma_f32_16x16x32_bf16 v[24:27], v[124:127], v[232:235], v[24:27]
	v_exp_f32_e32 v78, v78
	v_exp_f32_e32 v79, v79
	ds_read_b128 v[124:127], v96 offset:28672
	s_waitcnt lgkmcnt(7)
	v_mfma_f32_16x16x32_bf16 v[52:55], v[156:159], v[228:231], v[52:55]
	v_exp_f32_e32 v92, v92
	v_exp_f32_e32 v93, v93
	v_mfma_f32_16x16x32_bf16 v[24:27], v[156:159], v[236:239], v[24:27]
	v_exp_f32_e32 v94, v94
	v_exp_f32_e32 v95, v95
	ds_read_b128 v[156:159], v97 offset:28672
	s_waitcnt lgkmcnt(7)
	v_mfma_f32_16x16x32_bf16 v[60:63], v[188:191], v[184:187], v[60:63]
	v_exp_f32_e32 v80, v80
	v_exp_f32_e32 v81, v81
	v_mfma_f32_16x16x32_bf16 v[28:31], v[188:191], v[232:235], v[28:31]
	v_exp_f32_e32 v82, v82
	v_exp_f32_e32 v83, v83
	ds_read_b128 v[188:191], v96 offset:29184
	s_waitcnt lgkmcnt(7)
	v_mfma_f32_16x16x32_bf16 v[60:63], v[200:203], v[228:231], v[60:63]
	v_exp_f32_e32 v108, v108
	v_exp_f32_e32 v109, v109
	v_mfma_f32_16x16x32_bf16 v[28:31], v[200:203], v[236:239], v[28:31]
	v_exp_f32_e32 v110, v110
	v_exp_f32_e32 v111, v111
	ds_read_b128 v[200:203], v97 offset:29184
	s_cmp_eq_u32 s38, s48
	s_cbranch_scc0 .Lattn_nofix2
	v_cmp_le_i32_e64 s[50:51], 0, v103
	v_cmp_le_i32_e64 s[52:53], 1, v103
	v_cmp_le_i32_e64 s[56:57], 2, v103
	v_cndmask_b32_e64 v68, 0, v68, s[50:51]
	v_cndmask_b32_e64 v84, 0, v84, s[50:51]
	v_cmp_le_i32_e64 s[50:51], 3, v103
	v_cndmask_b32_e64 v69, 0, v69, s[52:53]
	v_cndmask_b32_e64 v85, 0, v85, s[52:53]
	v_cmp_le_i32_e64 s[52:53], 4, v103
	v_cndmask_b32_e64 v70, 0, v70, s[56:57]
	v_cndmask_b32_e64 v86, 0, v86, s[56:57]
	v_cmp_le_i32_e64 s[56:57], 5, v103
	v_cndmask_b32_e64 v71, 0, v71, s[50:51]
	v_cndmask_b32_e64 v87, 0, v87, s[50:51]
	v_cmp_le_i32_e64 s[50:51], 6, v103
	v_cndmask_b32_e64 v72, 0, v72, s[52:53]
	v_cndmask_b32_e64 v88, 0, v88, s[52:53]
	v_cmp_le_i32_e64 s[52:53], 7, v103
	v_cndmask_b32_e64 v73, 0, v73, s[56:57]
	v_cndmask_b32_e64 v89, 0, v89, s[56:57]
	v_cmp_le_i32_e64 s[56:57], 32, v103
	v_cndmask_b32_e64 v74, 0, v74, s[50:51]
	v_cndmask_b32_e64 v90, 0, v90, s[50:51]
	v_cmp_le_i32_e64 s[50:51], 33, v103
	v_cndmask_b32_e64 v75, 0, v75, s[52:53]
	v_cndmask_b32_e64 v91, 0, v91, s[52:53]
	v_cmp_le_i32_e64 s[52:53], 34, v103
	v_cndmask_b32_e64 v76, 0, v76, s[56:57]
	v_cndmask_b32_e64 v92, 0, v92, s[56:57]
	v_cmp_le_i32_e64 s[56:57], 35, v103
	v_cndmask_b32_e64 v77, 0, v77, s[50:51]
	v_cndmask_b32_e64 v93, 0, v93, s[50:51]
	v_cmp_le_i32_e64 s[50:51], 36, v103
	v_cndmask_b32_e64 v78, 0, v78, s[52:53]
	v_cndmask_b32_e64 v94, 0, v94, s[52:53]
	v_cmp_le_i32_e64 s[52:53], 37, v103
	v_cndmask_b32_e64 v79, 0, v79, s[56:57]
	v_cndmask_b32_e64 v95, 0, v95, s[56:57]
	v_cmp_le_i32_e64 s[56:57], 38, v103
	v_cndmask_b32_e64 v80, 0, v80, s[50:51]
	v_cndmask_b32_e64 v108, 0, v108, s[50:51]
	v_cmp_le_i32_e64 s[50:51], 39, v103
	v_cndmask_b32_e64 v81, 0, v81, s[52:53]
	v_cndmask_b32_e64 v109, 0, v109, s[52:53]
	v_cndmask_b32_e64 v82, 0, v82, s[56:57]
	v_cndmask_b32_e64 v110, 0, v110, s[56:57]
	v_cndmask_b32_e64 v83, 0, v83, s[50:51]
	v_cndmask_b32_e64 v111, 0, v111, s[50:51]

.Lattn_it3:
	s_waitcnt vmcnt(4) lgkmcnt(0)
	s_barrier
	s_add_i32 s46, s38, 4
	s_min_u32 s46, s46, s48
	s_lshl_b32 s42, s46, 14
	s_add_i32 s47, s38, 2
	s_min_u32 s47, s47, s48
	s_lshl_b32 s44, s47, 7
	v_lshl_add_u64 v[40:41], s[42:43], 0, v[106:107]
	v_lshl_add_u64 v[122:123], s[44:45], 0, v[114:115]
	v_mfma_f32_16x16x32_bf16 v[132:135], v[240:243], v[4:7], v[204:207]
	v_cvt_pk_bf16_f32 v184, v68, v69
	v_add_f32_e32 v112, v112, v68
	v_add_f32_e32 v113, v113, v84
	v_mfma_f32_16x16x32_bf16 v[148:151], v[240:243], v[12:15], v[204:207]
	v_cvt_pk_bf16_f32 v185, v70, v71
	v_add_f32_e32 v112, v112, v69
	v_add_f32_e32 v113, v113, v85
	ds_read_b128 v[240:243], v98 offset:49152
	s_add_i32 m0, s40, 0x6000
	s_nop 0
	global_load_lds_dwordx4 v[40:41], off
	v_mfma_f32_16x16x32_bf16 v[132:135], v[244:247], v[8:11], v[132:135]
	v_cvt_pk_bf16_f32 v186, v72, v73
	v_add_f32_e32 v112, v112, v70
	v_add_f32_e32 v113, v113, v86
	v_mfma_f32_16x16x32_bf16 v[148:151], v[244:247], v[16:19], v[148:151]
	v_cvt_pk_bf16_f32 v187, v74, v75
	v_add_f32_e32 v112, v112, v71
	v_add_f32_e32 v113, v113, v87
	ds_read_b128 v[244:247], v102 offset:49152
	s_add_i32 m0, s41, 0x2000
	s_nop 0
	global_load_lds_dwordx4 v[122:123], off
	v_mfma_f32_16x16x32_bf16 v[136:139], v[248:251], v[4:7], v[204:207]
	v_cvt_pk_bf16_f32 v228, v76, v77
	v_add_f32_e32 v112, v112, v72
	v_add_f32_e32 v113, v113, v88
	v_mfma_f32_16x16x32_bf16 v[152:155], v[248:251], v[12:15], v[204:207]
	v_cvt_pk_bf16_f32 v229, v78, v79
	v_add_f32_e32 v112, v112, v73
	v_add_f32_e32 v113, v113, v89
	ds_read_b128 v[248:251], v98 offset:51200
	v_mfma_f32_16x16x32_bf16 v[136:139], v[116:119], v[8:11], v[136:139]
	v_cvt_pk_bf16_f32 v230, v80, v81
	v_add_f32_e32 v112, v112, v74
	v_add_f32_e32 v113, v113, v90
	v_mfma_f32_16x16x32_bf16 v[152:155], v[116:119], v[16:19], v[152:155]
	v_cvt_pk_bf16_f32 v231, v82, v83
	v_add_f32_e32 v112, v112, v75
	v_add_f32_e32 v113, v113, v91
	ds_read_b128 v[116:119], v102 offset:51200
	v_mfma_f32_16x16x32_bf16 v[140:143], v[124:127], v[4:7], v[204:207]
	v_cvt_pk_bf16_f32 v232, v84, v85
	v_add_f32_e32 v112, v112, v76
	v_add_f32_e32 v113, v113, v92
	v_mfma_f32_16x16x32_bf16 v[176:179], v[124:127], v[12:15], v[204:207]
	v_cvt_pk_bf16_f32 v233, v86, v87
	v_add_f32_e32 v112, v112, v77
	v_add_f32_e32 v113, v113, v93
	ds_read_b128 v[124:127], v98 offset:53248
	v_mfma_f32_16x16x32_bf16 v[140:143], v[156:159], v[8:11], v[140:143]
	v_cvt_pk_bf16_f32 v234, v88, v89
	v_add_f32_e32 v112, v112, v78
	v_add_f32_e32 v113, v113, v94
	v_mfma_f32_16x16x32_bf16 v[176:179], v[156:159], v[16:19], v[176:179]
	v_cvt_pk_bf16_f32 v235, v90, v91
	v_add_f32_e32 v112, v112, v79
	v_add_f32_e32 v113, v113, v95
	ds_read_b128 v[156:159], v102 offset:53248
	v_mfma_f32_16x16x32_bf16 v[144:147], v[188:191], v[4:7], v[204:207]
	v_cvt_pk_bf16_f32 v236, v92, v93
	v_add_f32_e32 v112, v112, v80
	v_add_f32_e32 v113, v113, v108
	v_mfma_f32_16x16x32_bf16 v[180:183], v[188:191], v[12:15], v[204:207]
	v_cvt_pk_bf16_f32 v237, v94, v95
	v_add_f32_e32 v112, v112, v81
	v_add_f32_e32 v113, v113, v109
	ds_read_b128 v[188:191], v98 offset:55296
	v_mfma_f32_16x16x32_bf16 v[144:147], v[200:203], v[8:11], v[144:147]
	v_cvt_pk_bf16_f32 v238, v108, v109
	v_add_f32_e32 v112, v112, v82
	v_add_f32_e32 v113, v113, v110
	v_mfma_f32_16x16x32_bf16 v[180:183], v[200:203], v[16:19], v[180:183]
	v_cvt_pk_bf16_f32 v239, v110, v111
	v_add_f32_e32 v112, v112, v83
	v_add_f32_e32 v113, v113, v111
	ds_read_b128 v[200:203], v102 offset:55296
	s_waitcnt lgkmcnt(7)
	v_mfma_f32_16x16x32_bf16 v[64:67], v[240:243], v[184:187], v[64:67]
	v_exp_f32_e32 v132, v132
	v_exp_f32_e32 v133, v133
	v_mfma_f32_16x16x32_bf16 v[36:39], v[240:243], v[232:235], v[36:39]
	v_exp_f32_e32 v134, v134
	v_exp_f32_e32 v135, v135
	ds_read_b128 v[240:243], v96 offset:0
	s_waitcnt lgkmcnt(7)
	v_mfma_f32_16x16x32_bf16 v[64:67], v[244:247], v[228:231], v[64:67]
	v_exp_f32_e32 v148, v148
	v_exp_f32_e32 v149, v149
	v_mfma_f32_16x16x32_bf16 v[36:39], v[244:247], v[236:239], v[36:39]
	v_exp_f32_e32 v150, v150
	v_exp_f32_e32 v151, v151
	ds_read_b128 v[244:247], v97 offset:0
	s_waitcnt lgkmcnt(7)
	v_mfma_f32_16x16x32_bf16 v[56:59], v[248:251], v[184:187], v[56:59]
	v_exp_f32_e32 v136, v136
	v_exp_f32_e32 v137, v137
	v_mfma_f32_16x16x32_bf16 v[32:35], v[248:251], v[232:235], v[32:35]
	v_exp_f32_e32 v138, v138
	v_exp_f32_e32 v139, v139
	ds_read_b128 v[248:251], v96 offset:512
	s_waitcnt lgkmcnt(7)
	v_mfma_f32_16x16x32_bf16 v[56:59], v[116:119], v[228:231], v[56:59]
	v_exp_f32_e32 v152, v152
	v_exp_f32_e32 v153, v153
	v_mfma_f32_16x16x32_bf16 v[32:35], v[116:119], v[236:239], v[32:35]
	v_exp_f32_e32 v154, v154
	v_exp_f32_e32 v155, v155
	ds_read_b128 v[116:119], v97 offset:512
	s_waitcnt lgkmcnt(7)
	v_mfma_f32_16x16x32_bf16 v[52:55], v[124:127], v[184:187], v[52:55]
	v_exp_f32_e32 v140, v140
	v_exp_f32_e32 v141, v141
	v_mfma_f32_16x16x32_bf16 v[24:27], v[124:127], v[232:235], v[24:27]
	v_exp_f32_e32 v142, v142
	v_exp_f32_e32 v143, v143
	ds_read_b128 v[124:127], v96 offset:4096
	s_waitcnt lgkmcnt(7)
	v_mfma_f32_16x16x32_bf16 v[52:55], v[156:159], v[228:231], v[52:55]
	v_exp_f32_e32 v176, v176
	v_exp_f32_e32 v177, v177
	v_mfma_f32_16x16x32_bf16 v[24:27], v[156:159], v[236:239], v[24:27]
	v_exp_f32_e32 v178, v178
	v_exp_f32_e32 v179, v179
	ds_read_b128 v[156:159], v97 offset:4096
	s_waitcnt lgkmcnt(7)
	v_mfma_f32_16x16x32_bf16 v[60:63], v[188:191], v[184:187], v[60:63]
	v_exp_f32_e32 v144, v144
	v_exp_f32_e32 v145, v145
	v_mfma_f32_16x16x32_bf16 v[28:31], v[188:191], v[232:235], v[28:31]
	v_exp_f32_e32 v146, v146
	v_exp_f32_e32 v147, v147
	ds_read_b128 v[188:191], v96 offset:4608
	s_waitcnt lgkmcnt(7)
	v_mfma_f32_16x16x32_bf16 v[60:63], v[200:203], v[228:231], v[60:63]
	v_exp_f32_e32 v180, v180
	v_exp_f32_e32 v181, v181
	v_mfma_f32_16x16x32_bf16 v[28:31], v[200:203], v[236:239], v[28:31]
	v_exp_f32_e32 v182, v182
	v_exp_f32_e32 v183, v183
	ds_read_b128 v[200:203], v97 offset:4608
	s_cmp_eq_u32 s38, s48
	s_cbranch_scc0 .Lattn_nofix3
	v_cmp_le_i32_e64 s[50:51], 0, v103
	v_cmp_le_i32_e64 s[52:53], 1, v103
	v_cmp_le_i32_e64 s[56:57], 2, v103
	v_cndmask_b32_e64 v132, 0, v132, s[50:51]
	v_cndmask_b32_e64 v148, 0, v148, s[50:51]
	v_cmp_le_i32_e64 s[50:51], 3, v103
	v_cndmask_b32_e64 v133, 0, v133, s[52:53]
	v_cndmask_b32_e64 v149, 0, v149, s[52:53]
	v_cmp_le_i32_e64 s[52:53], 4, v103
	v_cndmask_b32_e64 v134, 0, v134, s[56:57]
	v_cndmask_b32_e64 v150, 0, v150, s[56:57]
	v_cmp_le_i32_e64 s[56:57], 5, v103
	v_cndmask_b32_e64 v135, 0, v135, s[50:51]
	v_cndmask_b32_e64 v151, 0, v151, s[50:51]
	v_cmp_le_i32_e64 s[50:51], 6, v103
	v_cndmask_b32_e64 v136, 0, v136, s[52:53]
	v_cndmask_b32_e64 v152, 0, v152, s[52:53]
	v_cmp_le_i32_e64 s[52:53], 7, v103
	v_cndmask_b32_e64 v137, 0, v137, s[56:57]
	v_cndmask_b32_e64 v153, 0, v153, s[56:57]
	v_cmp_le_i32_e64 s[56:57], 32, v103
	v_cndmask_b32_e64 v138, 0, v138, s[50:51]
	v_cndmask_b32_e64 v154, 0, v154, s[50:51]
	v_cmp_le_i32_e64 s[50:51], 33, v103
	v_cndmask_b32_e64 v139, 0, v139, s[52:53]
	v_cndmask_b32_e64 v155, 0, v155, s[52:53]
	v_cmp_le_i32_e64 s[52:53], 34, v103
	v_cndmask_b32_e64 v140, 0, v140, s[56:57]
	v_cndmask_b32_e64 v176, 0, v176, s[56:57]
	v_cmp_le_i32_e64 s[56:57], 35, v103
	v_cndmask_b32_e64 v141, 0, v141, s[50:51]
	v_cndmask_b32_e64 v177, 0, v177, s[50:51]
	v_cmp_le_i32_e64 s[50:51], 36, v103
	v_cndmask_b32_e64 v142, 0, v142, s[52:53]
	v_cndmask_b32_e64 v178, 0, v178, s[52:53]
	v_cmp_le_i32_e64 s[52:53], 37, v103
	v_cndmask_b32_e64 v143, 0, v143, s[56:57]
	v_cndmask_b32_e64 v179, 0, v179, s[56:57]
	v_cmp_le_i32_e64 s[56:57], 38, v103
	v_cndmask_b32_e64 v144, 0, v144, s[50:51]
	v_cndmask_b32_e64 v180, 0, v180, s[50:51]
	v_cmp_le_i32_e64 s[50:51], 39, v103
	v_cndmask_b32_e64 v145, 0, v145, s[52:53]
	v_cndmask_b32_e64 v181, 0, v181, s[52:53]
	v_cndmask_b32_e64 v146, 0, v146, s[56:57]
	v_cndmask_b32_e64 v182, 0, v182, s[56:57]
	v_cndmask_b32_e64 v147, 0, v147, s[50:51]
	v_cndmask_b32_e64 v183, 0, v183, s[50:51]

.Lattn_nosw3:
	v_lshrrev_b64 v[160:161], s38, v[198:199]
	v_and_b32_e32 v160, 1, v160
	v_cmp_eq_u32_e64 s[50:51], 1, v160
	s_nop 1
	v_cndmask_b32_e64 v204, v197, v42, s[50:51]
	v_mov_b32_e32 v205, v204
	v_mov_b32_e32 v206, v204
	v_mov_b32_e32 v207, v204
	s_branch .Lattn_it0
.Lattn_done:
	s_waitcnt vmcnt(0) lgkmcnt(0)
	s_barrier
	v_mov_b64_e32 v[156:157], 0xff
	v_mov_b64_e32 v[158:159], 0x580
	v_mov_b64_e32 v[160:161], 0x57f
	v_mov_b32_e32 v188, 0x358637bd
	v_mov_b32_e32 v189, 0x3dcccccd
	v_mov_b32_e32 v190, 0x3c0881c4
	v_mov_b32_e32 v191, 0xbab64f3b
	v_not_b32_e32 v200, 31
	v_mov_b32_e32 v201, 0x7fc00000
	v_mov_b32_e32 v202, 0x3e38aa3b
	v_mov_b32_e32 v203, 0xb0
	v_mov_b32_e32 v204, 0xb1
	v_mov_b32_e32 v205, 0x410
	v_mov_b32_e32 v206, 0x820
	v_mov_b32_e32 v207, 0xc30
	s_cmp_eq_u32 s37, 1
	s_cbranch_scc1 .Lattn_ret1
.Lattn_ret0:
.LBB0_182:
	ds_bpermute_b32 v0, v217, v112
	v_readlane_b32 s13, v254, 62
	s_lshl_b32 s2, s92, 20
	s_max_i32 s3, s13, 0x200
	s_lshl_b32 s0, s93, 13
	s_waitcnt lgkmcnt(0)
	v_add_f32_e32 v0, v112, v0
	ds_bpermute_b32 v2, v218, v0
	s_add_i32 s12, s3, 0xfffffe00
	s_lshl_b32 s2, s2, 1
	s_waitcnt lgkmcnt(0)
	v_add_f32_e32 v0, v0, v2
	ds_bpermute_b32 v2, v217, v113
	s_waitcnt lgkmcnt(0)
	v_add_f32_e32 v2, v113, v2
	ds_bpermute_b32 v3, v218, v2
	s_waitcnt lgkmcnt(0)
	v_add_f32_e32 v2, v2, v3
	global_load_ushort v3, v[130:131], off offset:2562
	s_waitcnt vmcnt(0)
	v_lshlrev_b32_e32 v3, 16, v3
	v_mul_f32_e32 v3, 0xbfb8aa3b, v3
	v_exp_f32_e32 v3, v3
	s_nop 0
	v_add_f32_e32 v3, 1.0, v3
	v_div_scale_f32 v20, s[8:9], v3, v3, 1.0
	v_rcp_f32_e32 v21, v20
	s_nop 0
	v_fma_f32 v22, -v20, v21, 1.0
	v_fmac_f32_e32 v21, v22, v21
	v_div_scale_f32 v22, vcc, 1.0, v3, 1.0
	v_mul_f32_e32 v23, v22, v21
	v_fma_f32 v40, -v20, v23, v22
	v_fmac_f32_e32 v23, v40, v21
	v_fma_f32 v20, -v20, v23, v22
	v_div_fmas_f32 v20, v20, v21, v23
	v_div_fixup_f32 v3, v20, v3, 1.0
	v_div_scale_f32 v20, s[8:9], v0, v0, v3
	v_rcp_f32_e32 v21, v20
	s_nop 0
	v_fma_f32 v22, -v20, v21, 1.0
	v_fmac_f32_e32 v21, v22, v21
	v_div_scale_f32 v22, vcc, v3, v0, v3
	v_mul_f32_e32 v23, v22, v21
	v_fma_f32 v40, -v20, v23, v22
	v_fmac_f32_e32 v23, v40, v21
	v_fma_f32 v20, -v20, v23, v22
	v_div_fmas_f32 v20, v20, v21, v23
	v_div_fixup_f32 v0, v20, v0, v3
	ds_read_b128 v[20:23], v224
	s_waitcnt lgkmcnt(0)
	v_pk_fma_f32 v[22:23], v[66:67], v[0:1], v[22:23] op_sel_hi:[1,0,1]
	v_pk_fma_f32 v[20:21], v[64:65], v[0:1], v[20:21] op_sel_hi:[1,0,1]
	ds_write_b128 v224, v[20:23]
	ds_read_b128 v[20:23], v224 offset:1024
	s_waitcnt lgkmcnt(0)
	v_pk_fma_f32 v[22:23], v[58:59], v[0:1], v[22:23] op_sel_hi:[1,0,1]
	v_pk_fma_f32 v[20:21], v[56:57], v[0:1], v[20:21] op_sel_hi:[1,0,1]
	ds_write_b128 v224, v[20:23] offset:1024
	ds_read_b128 v[20:23], v224 offset:2048
	s_waitcnt lgkmcnt(0)
	v_pk_fma_f32 v[22:23], v[54:55], v[0:1], v[22:23] op_sel_hi:[1,0,1]
	v_pk_fma_f32 v[20:21], v[52:53], v[0:1], v[20:21] op_sel_hi:[1,0,1]
	ds_write_b128 v224, v[20:23] offset:2048
	ds_read_b128 v[20:23], v224 offset:3072
	s_waitcnt lgkmcnt(0)
	v_pk_fma_f32 v[22:23], v[62:63], v[0:1], v[22:23] op_sel_hi:[1,0,1]
	v_pk_fma_f32 v[20:21], v[60:61], v[0:1], v[20:21] op_sel_hi:[1,0,1]
	global_load_ushort v0, v[130:131], off offset:2568
	ds_write_b128 v224, v[20:23] offset:3072
	s_waitcnt vmcnt(0)
	v_lshlrev_b32_e32 v0, 16, v0
	v_mul_f32_e32 v0, 0xbfb8aa3b, v0
	v_exp_f32_e32 v0, v0
	s_nop 0
	v_add_f32_e32 v0, 1.0, v0
	v_div_scale_f32 v3, s[8:9], v0, v0, 1.0
	v_rcp_f32_e32 v20, v3
	s_nop 0
	v_fma_f32 v21, -v3, v20, 1.0
	v_fmac_f32_e32 v20, v21, v20
	v_div_scale_f32 v21, vcc, 1.0, v0, 1.0
	v_mul_f32_e32 v22, v21, v20
	v_fma_f32 v23, -v3, v22, v21
	v_fmac_f32_e32 v22, v23, v20
	v_fma_f32 v3, -v3, v22, v21
	v_div_fmas_f32 v3, v3, v20, v22
	v_div_fixup_f32 v0, v3, v0, 1.0
	v_div_scale_f32 v3, s[8:9], v2, v2, v0
	v_rcp_f32_e32 v20, v3
	v_readlane_b32 s8, v253, 28
	s_add_u32 s2, s8, s2
	v_readlane_b32 s8, v253, 29
	v_fma_f32 v21, -v3, v20, 1.0
	v_fmac_f32_e32 v20, v21, v20
	v_div_scale_f32 v21, vcc, v0, v2, v0
	v_mul_f32_e32 v22, v21, v20
	v_fma_f32 v23, -v3, v22, v21
	v_fmac_f32_e32 v22, v23, v20
	v_fma_f32 v3, -v3, v22, v21
	v_div_fmas_f32 v3, v3, v20, v22
	ds_read_b128 v[20:23], v224 offset:4096
	v_div_fixup_f32 v0, v3, v2, v0
	s_addc_u32 s9, s8, 0
	s_add_u32 s8, s2, s6
	s_addc_u32 s9, s9, 0
	s_waitcnt lgkmcnt(0)
	v_pk_fma_f32 v[22:23], v[38:39], v[0:1], v[22:23] op_sel_hi:[1,0,1]
	v_pk_fma_f32 v[20:21], v[36:37], v[0:1], v[20:21] op_sel_hi:[1,0,1]
	ds_write_b128 v224, v[20:23] offset:4096
	ds_read_b128 v[20:23], v224 offset:5120
	s_lshl_b32 s0, s0, 1
	v_readlane_b32 s2, v253, 32
	s_add_u32 s26, s2, s0
	v_readlane_b32 s0, v253, 33
	s_waitcnt lgkmcnt(0)
	v_pk_fma_f32 v[22:23], v[34:35], v[0:1], v[22:23] op_sel_hi:[1,0,1]
	v_pk_fma_f32 v[20:21], v[32:33], v[0:1], v[20:21] op_sel_hi:[1,0,1]
	ds_write_b128 v224, v[20:23] offset:5120
	ds_read_b128 v[20:23], v224 offset:6144
	s_addc_u32 s27, s0, 0
	s_sub_i32 s0, s13, s3
	s_addk_i32 s0, 0x240
	s_ashr_i32 s6, s0, 6
	s_waitcnt lgkmcnt(0)
	v_pk_fma_f32 v[22:23], v[26:27], v[0:1], v[22:23] op_sel_hi:[1,0,1]
	v_pk_fma_f32 v[20:21], v[24:25], v[0:1], v[20:21] op_sel_hi:[1,0,1]
	ds_write_b128 v224, v[20:23] offset:6144
	ds_read_b128 v[20:23], v224 offset:7168
	v_mov_b32_e32 v24, v210
	s_mov_b32 s13, s1
	s_movk_i32 s0, 0x90
	s_cmp_gt_i32 s6, 0
	s_waitcnt lgkmcnt(0)
	v_pk_fma_f32 v[20:21], v[28:29], v[0:1], v[20:21] op_sel_hi:[1,0,1]
	v_pk_fma_f32 v[22:23], v[30:31], v[0:1], v[22:23] op_sel_hi:[1,0,1]
	v_mov_b32_e32 v0, v162
	ds_write_b128 v224, v[20:23] offset:7168
	s_cselect_b64 s[36:37], -1, 0
	v_ashrrev_i32_e32 v20, 3, v0
	v_ashrrev_i32_e32 v21, 31, v20
	v_lshlrev_b64 v[22:23], 14, v[20:21]
	v_lshlrev_b32_e32 v0, 4, v0
	v_lshl_add_u64 v[22:23], s[26:27], 0, v[22:23]
	v_and_b32_e32 v0, 0x70, v0
	v_lshl_add_u64 v[22:23], s[12:13], 1, v[22:23]
	v_mul_lo_u32 v3, v20, s0
	v_add_u32_e32 v2, s12, v20
	v_lshl_add_u64 v[130:131], s[8:9], 0, v[0:1]
	v_lshl_add_u64 v[132:133], v[22:23], 0, v[0:1]
	s_and_b64 vcc, exec, s[36:37]
	v_add3_u32 v129, 0, v3, v0
	s_cbranch_vccz .LBB0_184
	v_ashrrev_i32_e32 v3, 31, v2
	v_lshlrev_b64 v[20:21], 8, v[2:3]
	v_lshl_add_u64 v[20:21], v[130:131], 0, v[20:21]
	global_load_dwordx4 v[20:23], v[20:21], off
	s_nop 0
	global_load_dwordx4 v[26:29], v[132:133], off
	s_waitcnt vmcnt(1)
	ds_write_b128 v129, v[20:23]
	s_waitcnt vmcnt(0)
	ds_write_b128 v129, v[26:29] offset:9216

.LBB0_195:
	s_add_i32 s30, s15, s0
	v_add3_u32 v32, s30, v138, v139
	s_waitcnt lgkmcnt(7)
	ds_read_b128 v[124:127], v32
	s_waitcnt lgkmcnt(7)
	ds_read_b128 v[120:123], v32 offset:64
	s_waitcnt lgkmcnt(7)
	ds_read_b128 v[116:119], v32 offset:2304
	s_waitcnt lgkmcnt(7)
	ds_read_b128 v[96:99], v32 offset:2368
	s_waitcnt lgkmcnt(7)
	ds_read_b128 v[100:103], v32 offset:4608
	s_waitcnt lgkmcnt(7)
	ds_read_b128 v[104:107], v32 offset:4672
	s_waitcnt lgkmcnt(7)
	ds_read_b128 v[108:111], v32 offset:6912
	s_waitcnt lgkmcnt(7)
	ds_read_b128 v[112:115], v32 offset:6976
	s_lshl_b32 s31, s31, 6
	s_add_i32 s31, s31, s12
	v_sub_u32_e32 v32, s31, v3
	v_cmp_lt_u32_e32 vcc, s96, v32
	s_cbranch_vccz .LBB0_200
	s_waitcnt lgkmcnt(7)
	v_mfma_f32_16x16x32_bf16 v[32:35], v[124:127], v[4:7], v[20:23]
	v_add_u32_e32 v64, s31, v140
	v_add_u32_e32 v80, 1, v64
	v_cmp_gt_u32_e64 s[58:59], s22, v64
	s_waitcnt lgkmcnt(6)
	v_mfma_f32_16x16x32_bf16 v[32:35], v[120:123], v[8:11], v[32:35]
	v_cmp_gt_u32_e64 s[56:57], s22, v80
	v_add_u32_e32 v81, 2, v64
	v_add_u32_e32 v82, 3, v64
	s_waitcnt lgkmcnt(5)
	v_mfma_f32_16x16x32_bf16 v[36:39], v[116:119], v[4:7], v[20:23]
	v_cmp_gt_u32_e64 s[60:61], s22, v81
	s_nop 1
	v_exp_f32_e32 v32, v32
	v_exp_f32_e32 v33, v33
	s_waitcnt lgkmcnt(4)
	v_mfma_f32_16x16x32_bf16 v[36:39], v[96:99], v[8:11], v[36:39]
	v_cmp_gt_u32_e64 s[62:63], s22, v82
	v_cndmask_b32_e64 v95, 0, v32, s[58:59]
	v_cndmask_b32_e64 v80, 0, v33, s[56:57]
	v_exp_f32_e32 v32, v34
	v_exp_f32_e32 v33, v35
	s_waitcnt lgkmcnt(3)
	v_mfma_f32_16x16x32_bf16 v[60:63], v[100:103], v[4:7], v[20:23]
	v_add_u32_e32 v83, 16, v64
	v_cndmask_b32_e64 v81, 0, v32, s[60:61]
	v_exp_f32_e32 v32, v36
	v_cndmask_b32_e64 v82, 0, v33, s[62:63]
	v_exp_f32_e32 v33, v37
	v_add_u32_e32 v84, 17, v64
	v_cmp_gt_u32_e64 s[64:65], s22, v83
	v_cmp_gt_u32_e64 s[48:49], s22, v84
	s_waitcnt lgkmcnt(2)
	v_mfma_f32_16x16x32_bf16 v[60:63], v[104:107], v[8:11], v[60:63]
	v_cndmask_b32_e64 v83, 0, v32, s[64:65]
	v_exp_f32_e32 v32, v38
	v_cndmask_b32_e64 v84, 0, v33, s[48:49]
	v_exp_f32_e32 v33, v39
	v_add_u32_e32 v85, 18, v64
	v_add_u32_e32 v86, 19, v64
	v_cmp_gt_u32_e64 s[50:51], s22, v85
	v_cmp_gt_u32_e64 s[52:53], s22, v86
	v_add_u32_e32 v87, 32, v64
	v_add_u32_e32 v88, 33, v64
	v_add_u32_e32 v89, 34, v64
	v_add_u32_e32 v90, 35, v64
	v_add_u32_e32 v91, 48, v64
	v_add_u32_e32 v92, 49, v64
	v_add_u32_e32 v93, 50, v64
	v_add_u32_e32 v94, 51, v64
	s_waitcnt lgkmcnt(1)
	v_mfma_f32_16x16x32_bf16 v[64:67], v[108:111], v[4:7], v[20:23]
	v_cndmask_b32_e64 v85, 0, v32, s[50:51]
	v_exp_f32_e32 v32, v60
	v_cndmask_b32_e64 v86, 0, v33, s[52:53]
	v_exp_f32_e32 v33, v61
	v_cmp_gt_u32_e64 s[54:55], s22, v87
	v_cmp_gt_u32_e64 s[40:41], s22, v88
	s_waitcnt lgkmcnt(0)
	v_mfma_f32_16x16x32_bf16 v[64:67], v[112:115], v[8:11], v[64:67]
	v_cndmask_b32_e64 v87, 0, v32, s[54:55]
	v_exp_f32_e32 v32, v62
	v_cndmask_b32_e64 v88, 0, v33, s[40:41]
	v_exp_f32_e32 v33, v63
	v_cmp_gt_u32_e32 vcc, s22, v89
	v_cmp_gt_u32_e64 s[38:39], s22, v90
	v_cmp_gt_u32_e64 s[46:47], s22, v91
	v_cndmask_b32_e32 v89, 0, v32, vcc
	v_exp_f32_e32 v32, v64
	v_cndmask_b32_e64 v90, 0, v33, s[38:39]
	v_exp_f32_e32 v33, v65
	v_cmp_gt_u32_e64 s[36:37], s22, v92
	v_cndmask_b32_e64 v91, 0, v32, s[46:47]
	v_exp_f32_e32 v32, v66
	v_cndmask_b32_e64 v92, 0, v33, s[36:37]
	v_exp_f32_e32 v33, v67
	v_cmp_gt_u32_e64 s[42:43], s22, v93
	v_cmp_gt_u32_e64 s[44:45], s22, v94
	v_add_f32_e32 v37, v83, v84
	v_cndmask_b32_e64 v93, 0, v32, s[42:43]
	v_cndmask_b32_e64 v94, 0, v33, s[44:45]
	v_add_f32_e32 v32, v95, v80
	v_add_f32_e32 v33, v81, v82
	v_add_f32_e32 v38, v85, v86
	v_add_f32_e32 v36, v32, v33
	v_add_f32_e32 v37, v37, v38
	v_mfma_f32_16x16x32_bf16 v[32:35], v[124:127], v[12:15], v[20:23]
	v_add_f32_e32 v60, v36, v37
	v_add_f32_e32 v36, v87, v88
	v_add_f32_e32 v37, v89, v90
	v_add_f32_e32 v62, v91, v92
	v_add_f32_e32 v63, v93, v94
	v_add_f32_e32 v61, v36, v37
	v_add_f32_e32 v62, v62, v63
	v_add_f32_e32 v61, v61, v62
	v_add_f32_e32 v60, v60, v61
	v_mfma_f32_16x16x32_bf16 v[32:35], v[120:123], v[16:19], v[32:35]
	v_add_f32_e32 v136, v134, v60
	v_add3_u32 v174, s30, v141, v139
	v_add_u32_e32 v227, 0x2800, v174
	v_mfma_f32_16x16x32_bf16 v[36:39], v[116:119], v[12:15], v[20:23]
	v_cvt_pk_bf16_f32 v64, v95, v80
	s_nop 2
	v_exp_f32_e32 v32, v32
	v_cvt_pk_bf16_f32 v65, v81, v82
	v_mfma_f32_16x16x32_bf16 v[60:63], v[100:103], v[12:15], v[20:23]
	v_cvt_pk_bf16_f32 v66, v83, v84
	v_cndmask_b32_e64 v137, 0, v32, s[58:59]
	v_exp_f32_e32 v32, v33
	v_mfma_f32_16x16x32_bf16 v[36:39], v[96:99], v[16:19], v[36:39]
	v_exp_f32_e32 v33, v34
	v_exp_f32_e32 v34, v35
	v_cvt_pk_bf16_f32 v67, v85, v86
	v_mfma_f32_16x16x32_bf16 v[60:63], v[104:107], v[16:19], v[60:63]
	v_cvt_pk_bf16_f32 v80, v87, v88
	s_nop 2
	v_exp_f32_e32 v35, v36
	v_exp_f32_e32 v36, v37
	v_exp_f32_e32 v37, v38
	v_exp_f32_e32 v38, v39
	v_exp_f32_e32 v39, v60
	v_exp_f32_e32 v60, v61
	v_cvt_pk_bf16_f32 v81, v89, v90
	v_mfma_f32_16x16x32_bf16 v[84:87], v[108:111], v[12:15], v[20:23]
	v_cvt_pk_bf16_f32 v82, v91, v92
	ds_read_b64 v[88:89], v227 offset:1280
	ds_read_b64 v[90:91], v227 offset:1312
	v_add_u32_e32 v180, 0x2000, v174
	v_add_u32_e32 v230, 0x3000, v174
	v_add_u32_e32 v174, 0x3800, v174
	v_cndmask_b32_e64 v143, 0, v32, s[56:57]
	v_cndmask_b32_e64 v171, 0, v33, s[60:61]
	v_cndmask_b32_e64 v172, 0, v34, s[62:63]
	v_cndmask_b32_e64 v173, 0, v35, s[64:65]
	ds_read_b64 v[32:33], v180 offset:1024
	ds_read_b64 v[34:35], v180 offset:1056
	ds_read_b64 v[144:145], v230 offset:1536
	ds_read_b64 v[146:147], v230 offset:1568
	v_cndmask_b32_e64 v231, 0, v60, s[40:41]
	v_exp_f32_e32 v181, v62
	v_exp_f32_e32 v182, v63
	ds_read_b64 v[60:61], v174 offset:1792
	ds_read_b64 v[62:63], v174 offset:1824
	v_mfma_f32_16x16x32_bf16 v[84:87], v[112:115], v[16:19], v[84:87]
	v_cndmask_b32_e64 v193, 0, v36, s[48:49]
	v_cndmask_b32_e64 v198, 0, v37, s[50:51]
	v_cndmask_b32_e64 v199, 0, v38, s[52:53]
	v_cndmask_b32_e64 v225, 0, v39, s[54:55]
	v_cvt_pk_bf16_f32 v36, v137, v143
	v_cvt_pk_bf16_f32 v37, v171, v172
	v_cvt_pk_bf16_f32 v38, v173, v193
	v_cvt_pk_bf16_f32 v39, v198, v199
	v_exp_f32_e32 v84, v84
	s_waitcnt lgkmcnt(6)
	v_mfma_f32_16x16x32_bf16 v[148:151], v[88:91], v[64:67], v[68:71]
	v_cvt_pk_bf16_f32 v83, v93, v94
	v_cndmask_b32_e32 v232, 0, v181, vcc
	v_cndmask_b32_e64 v233, 0, v182, s[38:39]
	v_mfma_f32_16x16x32_bf16 v[152:155], v[88:91], v[36:39], v[56:59]
	ds_read_b64 v[88:89], v180 offset:1088
	ds_read_b64 v[90:91], v180 offset:1120
	v_cndmask_b32_e64 v234, 0, v84, s[46:47]
	v_exp_f32_e32 v84, v85
	s_waitcnt lgkmcnt(6)
	v_mfma_f32_16x16x32_bf16 v[92:95], v[32:35], v[64:67], v[76:79]
	v_exp_f32_e32 v85, v86
	v_cvt_pk_bf16_f32 v226, v225, v231
	v_cndmask_b32_e64 v235, 0, v84, s[36:37]
	s_waitcnt lgkmcnt(4)
	v_mfma_f32_16x16x32_bf16 v[176:179], v[144:147], v[64:67], v[52:55]
	v_cndmask_b32_e64 v236, 0, v85, s[42:43]
	v_cvt_pk_bf16_f32 v228, v234, v235
	s_waitcnt lgkmcnt(2)
	v_mfma_f32_16x16x32_bf16 v[180:183], v[60:63], v[64:67], v[44:47]
	v_exp_f32_e32 v64, v87
	v_add_f32_e32 v65, v171, v172
	v_cndmask_b32_e64 v237, 0, v64, s[44:45]
	v_mfma_f32_16x16x32_bf16 v[32:35], v[32:35], v[36:39], v[72:75]
	v_cvt_pk_bf16_f32 v229, v236, v237
	v_add_f32_e32 v64, v137, v143
	v_mfma_f32_16x16x32_bf16 v[144:147], v[144:147], v[36:39], v[48:51]
	v_mfma_f32_16x16x32_bf16 v[184:187], v[60:63], v[36:39], v[40:43]
	ds_read_b64 v[36:37], v227 offset:1344
	ds_read_b64 v[38:39], v227 offset:1376
	v_cvt_pk_bf16_f32 v227, v232, v233
	s_waitcnt lgkmcnt(2)
	v_mfma_f32_16x16x32_bf16 v[84:87], v[88:91], v[80:83], v[92:95]
	v_mfma_f32_16x16x32_bf16 v[60:63], v[88:91], v[226:229], v[32:35]
	s_nop 1
	v_add_f32_e32 v93, v173, v193
	v_add_f32_e32 v94, v198, v199
	v_add_f32_e32 v92, v64, v65
	ds_read_b64 v[32:33], v230 offset:1600
	ds_read_b64 v[34:35], v230 offset:1632
	s_waitcnt lgkmcnt(2)
	v_mfma_f32_16x16x32_bf16 v[88:91], v[36:39], v[80:83], v[148:151]
	s_nop 2
	ds_read_b64 v[148:149], v174 offset:1856
	ds_read_b64 v[150:151], v174 offset:1888
	v_mfma_f32_16x16x32_bf16 v[64:67], v[36:39], v[226:229], v[152:155]
	v_add_f32_e32 v36, v93, v94
	v_add_f32_e32 v137, v92, v36
	v_add_f32_e32 v36, v225, v231
	v_add_f32_e32 v37, v232, v233
	s_waitcnt lgkmcnt(2)
	v_mfma_f32_16x16x32_bf16 v[92:95], v[32:35], v[80:83], v[176:179]
	v_add_f32_e32 v143, v36, v37
	v_mfma_f32_16x16x32_bf16 v[36:39], v[32:35], v[226:229], v[144:147]
	v_add_f32_e32 v32, v234, v235
	v_add_f32_e32 v33, v236, v237
	v_add_f32_e32 v32, v32, v33
	v_add_f32_e32 v32, v143, v32
	v_add_f32_e32 v32, v137, v32
	s_waitcnt lgkmcnt(0)
	v_mfma_f32_16x16x32_bf16 v[80:83], v[148:151], v[80:83], v[180:183]
	v_add_f32_e32 v137, v135, v32
	v_mfma_f32_16x16x32_bf16 v[32:35], v[148:151], v[226:229], v[184:187]
	s_cbranch_execnz .LBB0_198
.LBB0_197:
	s_waitcnt lgkmcnt(7)
	v_mfma_f32_16x16x32_bf16 v[32:35], v[124:127], v[4:7], v[20:23]
	s_waitcnt lgkmcnt(5)
	v_mfma_f32_16x16x32_bf16 v[36:39], v[116:119], v[4:7], v[20:23]
	s_waitcnt lgkmcnt(3)
	v_mfma_f32_16x16x32_bf16 v[60:63], v[100:103], v[4:7], v[20:23]
	s_waitcnt lgkmcnt(1)
	v_mfma_f32_16x16x32_bf16 v[64:67], v[108:111], v[4:7], v[20:23]
	v_mfma_f32_16x16x32_bf16 v[32:35], v[120:123], v[8:11], v[32:35]
	v_mfma_f32_16x16x32_bf16 v[36:39], v[96:99], v[8:11], v[36:39]
	v_mfma_f32_16x16x32_bf16 v[60:63], v[104:107], v[8:11], v[60:63]
	s_nop 5
	v_exp_f32_e32 v32, v32
	v_exp_f32_e32 v80, v33
	v_exp_f32_e32 v34, v34
	s_waitcnt lgkmcnt(0)
	v_mfma_f32_16x16x32_bf16 v[64:67], v[112:115], v[8:11], v[64:67]
	v_exp_f32_e32 v82, v35
	v_exp_f32_e32 v33, v36
	v_exp_f32_e32 v81, v37
	v_exp_f32_e32 v35, v38
	v_exp_f32_e32 v83, v39
	v_exp_f32_e32 v60, v60
	v_exp_f32_e32 v84, v61
	v_exp_f32_e32 v62, v62
	v_exp_f32_e32 v86, v63
	v_exp_f32_e32 v61, v64
	v_exp_f32_e32 v85, v65
	v_exp_f32_e32 v63, v66
	v_exp_f32_e32 v87, v67
	v_pk_add_f32 v[36:37], v[32:33], v[80:81]
	v_pk_add_f32 v[38:39], v[34:35], v[82:83]
	v_mfma_f32_16x16x32_bf16 v[64:67], v[116:119], v[12:15], v[20:23]
	v_add_f32_e64 v36, v36, v38
	v_add_f32_e64 v37, v37, v39
	v_pk_add_f32 v[38:39], v[62:63], v[86:87]
	v_pk_add_f32 v[88:89], v[36:37], v[36:37] op_sel:[0,1] op_sel_hi:[1,0]
	v_pk_add_f32 v[36:37], v[60:61], v[84:85]
	v_mfma_f32_16x16x32_bf16 v[64:67], v[96:99], v[16:19], v[64:67]
	v_add_f32_e64 v36, v36, v38
	v_add_f32_e64 v37, v37, v39
	v_cvt_pk_bf16_f32 v38, v33, v81
	v_pk_add_f32 v[90:91], v[36:37], v[36:37] op_sel:[0,1] op_sel_hi:[1,0]
	v_cvt_pk_bf16_f32 v36, v32, v80
	v_cvt_pk_bf16_f32 v37, v34, v82
	v_cvt_pk_bf16_f32 v39, v35, v83
	v_cvt_pk_bf16_f32 v32, v60, v84
	v_cvt_pk_bf16_f32 v33, v62, v86
	v_cvt_pk_bf16_f32 v34, v61, v85
	v_cvt_pk_bf16_f32 v35, v63, v87
	v_mfma_f32_16x16x32_bf16 v[60:63], v[124:127], v[12:15], v[20:23]
	v_exp_f32_e32 v64, v64
	v_exp_f32_e32 v66, v66
	v_mfma_f32_16x16x32_bf16 v[80:83], v[100:103], v[12:15], v[20:23]
	v_exp_f32_e32 v100, v65
	v_exp_f32_e32 v102, v67
	v_mfma_f32_16x16x32_bf16 v[84:87], v[108:111], v[12:15], v[20:23]
	v_mfma_f32_16x16x32_bf16 v[60:63], v[120:123], v[16:19], v[60:63]
	v_mfma_f32_16x16x32_bf16 v[80:83], v[104:107], v[16:19], v[80:83]
	v_mfma_f32_16x16x32_bf16 v[84:87], v[112:115], v[16:19], v[84:87]
	s_nop 5
	v_exp_f32_e32 v92, v60
	v_exp_f32_e32 v94, v61
	v_exp_f32_e32 v96, v62
	v_exp_f32_e32 v98, v63
	v_exp_f32_e32 v93, v80
	v_exp_f32_e32 v95, v81
	v_exp_f32_e32 v97, v82
	v_exp_f32_e32 v99, v83
	v_exp_f32_e32 v65, v84
	v_exp_f32_e32 v101, v85
	v_exp_f32_e32 v67, v86
	v_exp_f32_e32 v103, v87
	v_pk_add_f32 v[60:61], v[92:93], v[94:95]
	v_pk_add_f32 v[62:63], v[96:97], v[98:99]
	v_cvt_pk_bf16_f32 v97, v97, v99
	v_pk_add_f32 v[60:61], v[60:61], v[62:63]
	v_pk_add_f32 v[62:63], v[64:65], v[100:101]
	v_pk_add_f32 v[80:81], v[66:67], v[102:103]
	v_cvt_pk_bf16_f32 v99, v67, v103
	v_pk_add_f32 v[62:63], v[62:63], v[80:81]
	s_nop 0
	v_pk_add_f32 v[60:61], v[60:61], v[62:63]
	v_cvt_pk_bf16_f32 v62, v64, v100
	v_mov_b32_e32 v89, v60
	v_mov_b32_e32 v91, v61
	v_pk_add_f32 v[60:61], v[88:89], v[90:91]
	v_add3_u32 v88, s30, v142, v139
	v_pk_add_f32 v[136:137], v[134:135], v[60:61]
	v_cvt_pk_bf16_f32 v60, v92, v94
	v_cvt_pk_bf16_f32 v61, v96, v98
	v_cvt_pk_bf16_f32 v96, v93, v95
	v_add_u32_e32 v92, 0x2000, v88
	v_add_u32_e32 v93, 0x2800, v88
	v_add_u32_e32 v94, 0x3000, v88
	v_add_u32_e32 v95, 0x3800, v88
	v_cvt_pk_bf16_f32 v63, v66, v102
	v_cvt_pk_bf16_f32 v98, v65, v101
	ds_read_b64 v[64:65], v92 offset:1024
	ds_read_b64 v[66:67], v92 offset:1056
	ds_read_b64 v[80:81], v93 offset:1280
	ds_read_b64 v[82:83], v93 offset:1312
	ds_read_b64 v[84:85], v94 offset:1536
	ds_read_b64 v[86:87], v94 offset:1568
	ds_read_b64 v[88:89], v95 offset:1792
	ds_read_b64 v[90:91], v95 offset:1824
	s_waitcnt lgkmcnt(6)
	v_mfma_f32_16x16x32_bf16 v[76:79], v[64:67], v[36:39], v[76:79]
	v_mfma_f32_16x16x32_bf16 v[64:67], v[64:67], v[60:63], v[72:75]
	s_waitcnt lgkmcnt(4)
	v_mfma_f32_16x16x32_bf16 v[68:71], v[80:83], v[36:39], v[68:71]
	v_mfma_f32_16x16x32_bf16 v[56:59], v[80:83], v[60:63], v[56:59]
	s_waitcnt lgkmcnt(2)
	v_mfma_f32_16x16x32_bf16 v[52:55], v[84:87], v[36:39], v[52:55]
	s_waitcnt lgkmcnt(0)
	v_mfma_f32_16x16x32_bf16 v[44:47], v[88:91], v[36:39], v[44:47]
	ds_read_b64 v[36:37], v92 offset:1088
	ds_read_b64 v[38:39], v92 offset:1120
	ds_read_b64 v[72:73], v93 offset:1344
	ds_read_b64 v[74:75], v93 offset:1376
	ds_read_b64 v[80:81], v94 offset:1600
	ds_read_b64 v[82:83], v94 offset:1632
	ds_read_b64 v[100:101], v95 offset:1856
	ds_read_b64 v[102:103], v95 offset:1888
	v_mfma_f32_16x16x32_bf16 v[48:51], v[84:87], v[60:63], v[48:51]
	v_mfma_f32_16x16x32_bf16 v[40:43], v[88:91], v[60:63], v[40:43]
	s_waitcnt lgkmcnt(6)
	v_mfma_f32_16x16x32_bf16 v[84:87], v[36:39], v[32:35], v[76:79]
	v_mfma_f32_16x16x32_bf16 v[60:63], v[36:39], v[96:99], v[64:67]
	s_waitcnt lgkmcnt(4)
	v_mfma_f32_16x16x32_bf16 v[88:91], v[72:75], v[32:35], v[68:71]
	v_mfma_f32_16x16x32_bf16 v[64:67], v[72:75], v[96:99], v[56:59]
	s_waitcnt lgkmcnt(2)
	v_mfma_f32_16x16x32_bf16 v[92:95], v[80:83], v[32:35], v[52:55]
	v_mfma_f32_16x16x32_bf16 v[36:39], v[80:83], v[96:99], v[48:51]
	s_waitcnt lgkmcnt(0)
	v_mfma_f32_16x16x32_bf16 v[80:83], v[100:103], v[32:35], v[44:47]
	v_mfma_f32_16x16x32_bf16 v[32:35], v[100:103], v[96:99], v[40:43]

.LBB0_226:
	s_add_i32 s31, s60, s0
	v_add3_u32 v2, s31, v177, v228
	s_waitcnt lgkmcnt(8)
	ds_read_b128 v[92:95], v2
	s_waitcnt lgkmcnt(8)
	ds_read_b128 v[88:91], v2 offset:64
	s_waitcnt lgkmcnt(8)
	ds_read_b128 v[84:87], v2 offset:2304
	s_waitcnt lgkmcnt(8)
	ds_read_b128 v[80:83], v2 offset:2368
	s_waitcnt lgkmcnt(8)
	ds_read_b128 v[76:79], v2 offset:4608
	s_waitcnt lgkmcnt(8)
	ds_read_b128 v[72:75], v2 offset:4672
	s_waitcnt lgkmcnt(8)
	ds_read_b128 v[68:71], v2 offset:6912
	s_waitcnt lgkmcnt(8)
	ds_read_b128 v[64:67], v2 offset:6976
	s_lshl_b32 s30, s30, 6
	s_or_b32 s38, s30, 63
	s_max_u32 s38, s30, s38
	v_add3_u32 v2, s31, v230, v228
	v_cmp_ge_u32_e32 vcc, s38, v174
	v_add_u32_e32 v235, s30, v232
	v_add_u32_e32 v239, 0x2000, v2
	v_add_u32_e32 v238, 0x2800, v2
	v_add_u32_e32 v237, 0x3000, v2
	v_add_u32_e32 v236, 0x3800, v2
	s_cbranch_vccz .LBB0_231
	v_add_u32_e32 v2, s30, v229
	v_or_b32_e32 v3, 1, v2
	v_cmp_lt_u32_e64 s[56:57], v3, v174
	v_or_b32_e32 v3, 2, v2
	v_cmp_lt_u32_e64 s[54:55], v3, v174
	v_or_b32_e32 v3, 3, v2
	v_cmp_lt_u32_e64 s[50:51], v3, v174
	v_add_u32_e32 v3, 16, v2
	s_waitcnt lgkmcnt(7)
	v_mfma_f32_16x16x32_bf16 v[96:99], v[92:95], v[4:7], v[20:23]
	v_cmp_lt_u32_e64 s[52:53], v3, v174
	v_add_u32_e32 v3, 17, v2
	v_cmp_lt_u32_e64 s[48:49], v3, v174
	v_add_u32_e32 v3, 18, v2
	v_cmp_lt_u32_e64 s[46:47], v3, v174
	v_add_u32_e32 v3, 19, v2
	v_cmp_lt_u32_e64 s[42:43], v3, v174
	v_add_u32_e32 v3, 32, v2
	s_waitcnt lgkmcnt(6)
	v_mfma_f32_16x16x32_bf16 v[96:99], v[88:91], v[8:11], v[96:99]
	v_cmp_lt_u32_e64 s[44:45], v3, v174
	v_add_u32_e32 v3, 33, v2
	v_cmp_lt_u32_e64 s[40:41], v3, v174
	v_add_u32_e32 v3, 34, v2
	v_cmp_lt_u32_e64 s[38:39], v3, v174
	v_add_u32_e32 v3, 35, v2
	v_cmp_lt_u32_e32 vcc, v3, v174
	s_nop 0
	v_exp_f32_e32 v3, v96
	v_cmp_lt_u32_e64 s[58:59], v2, v174
	s_waitcnt lgkmcnt(5)
	v_mfma_f32_16x16x32_bf16 v[100:103], v[84:87], v[4:7], v[20:23]
	v_cndmask_b32_e64 v96, 0, v3, s[58:59]
	v_exp_f32_e32 v3, v97
	s_waitcnt lgkmcnt(4)
	v_mfma_f32_16x16x32_bf16 v[100:103], v[80:83], v[8:11], v[100:103]
	v_fma_f32 v248, v182, v96, 0
	v_cndmask_b32_e64 v97, 0, v3, s[56:57]
	v_exp_f32_e32 v3, v98
	s_waitcnt lgkmcnt(3)
	v_mfma_f32_16x16x32_bf16 v[104:107], v[76:79], v[4:7], v[20:23]
	v_fma_f32 v249, v182, v97, 0
	v_cndmask_b32_e64 v98, 0, v3, s[54:55]
	v_exp_f32_e32 v3, v99
	s_waitcnt lgkmcnt(2)
	v_mfma_f32_16x16x32_bf16 v[104:107], v[72:75], v[8:11], v[104:107]
	v_fma_f32 v250, v182, v98, 0
	v_cndmask_b32_e64 v99, 0, v3, s[50:51]
	v_exp_f32_e32 v3, v100
	s_waitcnt lgkmcnt(1)
	v_mfma_f32_16x16x32_bf16 v[108:111], v[68:71], v[4:7], v[20:23]
	v_fma_f32 v247, v182, v99, 0
	v_cndmask_b32_e64 v100, 0, v3, s[52:53]
	v_exp_f32_e32 v3, v101
	s_waitcnt lgkmcnt(0)
	v_mfma_f32_16x16x32_bf16 v[108:111], v[64:67], v[8:11], v[108:111]
	v_fma_f32 v244, v182, v100, 0
	v_cndmask_b32_e64 v101, 0, v3, s[48:49]
	v_exp_f32_e32 v3, v102
	v_fma_f32 v245, v182, v101, 0
	s_nop 3
	v_exp_f32_e32 v115, v108
	v_mul_f32_e32 v108, v182, v96
	v_cndmask_b32_e64 v102, 0, v3, s[46:47]
	v_exp_f32_e32 v3, v103
	v_mul_f32_e32 v96, v182, v97
	v_mul_f32_e32 v97, v182, v98
	v_mul_f32_e32 v98, v182, v99
	v_cndmask_b32_e64 v103, 0, v3, s[42:43]
	v_exp_f32_e32 v3, v104
	v_mul_f32_e32 v99, v182, v100
	v_mul_f32_e32 v100, v182, v101
	v_mul_f32_e32 v101, v182, v102
	v_cndmask_b32_e64 v104, 0, v3, s[44:45]
	v_exp_f32_e32 v3, v105
	v_fma_f32 v246, v182, v102, 0
	v_mul_f32_e32 v102, v182, v103
	v_fma_f32 v240, v182, v103, 0
	v_cndmask_b32_e64 v105, 0, v3, s[40:41]
	v_exp_f32_e32 v3, v106
	v_mul_f32_e32 v103, v182, v104
	v_fma_f32 v131, v182, v104, 0
	v_mul_f32_e32 v104, v182, v105
	v_cndmask_b32_e64 v106, 0, v3, s[38:39]
	v_exp_f32_e32 v3, v107
	v_fma_f32 v241, v182, v105, 0
	v_mul_f32_e32 v105, v182, v106
	v_fma_f32 v242, v182, v106, 0
	v_cndmask_b32_e32 v107, 0, v3, vcc
	v_mul_f32_e32 v106, v182, v107
	v_exp_f32_e32 v114, v109
	v_exp_f32_e32 v130, v110
	v_exp_f32_e32 v3, v111
	v_fma_f32 v243, v182, v107, 0
	v_cvt_pk_bf16_f32 v96, v108, v96
	v_cvt_pk_bf16_f32 v97, v97, v98
	v_cvt_pk_bf16_f32 v98, v99, v100
	v_cvt_pk_bf16_f32 v99, v101, v102
	v_cvt_pk_bf16_f32 v108, v103, v104
	v_cvt_pk_bf16_f32 v109, v105, v106
	v_mfma_f32_16x16x32_bf16 v[100:103], v[92:95], v[12:15], v[20:23]
	v_mfma_f32_16x16x32_bf16 v[104:107], v[84:87], v[12:15], v[20:23]
	v_mfma_f32_16x16x32_bf16 v[110:113], v[76:79], v[12:15], v[20:23]
	v_mfma_f32_16x16x32_bf16 v[100:103], v[88:91], v[16:19], v[100:103]
	v_mfma_f32_16x16x32_bf16 v[104:107], v[80:83], v[16:19], v[104:107]
	v_mfma_f32_16x16x32_bf16 v[110:113], v[72:75], v[16:19], v[110:113]
	s_nop 5
	v_exp_f32_e32 v100, v100
	v_exp_f32_e32 v101, v101
	v_exp_f32_e32 v102, v102
	v_mfma_f32_16x16x32_bf16 v[116:119], v[68:71], v[12:15], v[20:23]
	v_exp_f32_e32 v103, v103
	v_exp_f32_e32 v104, v104
	v_exp_f32_e32 v105, v105
	v_exp_f32_e32 v106, v106
	v_exp_f32_e32 v107, v107
	v_exp_f32_e32 v110, v110
	v_exp_f32_e32 v111, v111
	v_mfma_f32_16x16x32_bf16 v[116:119], v[64:67], v[16:19], v[116:119]
	v_exp_f32_e32 v112, v112
	v_exp_f32_e32 v113, v113
	v_cndmask_b32_e64 v100, 0, v100, s[58:59]
	v_cndmask_b32_e64 v101, 0, v101, s[56:57]
	v_cndmask_b32_e64 v102, 0, v102, s[54:55]
	v_cndmask_b32_e64 v103, 0, v103, s[50:51]
	v_cndmask_b32_e64 v104, 0, v104, s[52:53]
	v_cndmask_b32_e64 v105, 0, v105, s[48:49]
	v_cndmask_b32_e64 v106, 0, v106, s[46:47]
	v_cndmask_b32_e64 v107, 0, v107, s[42:43]
	v_cndmask_b32_e64 v110, 0, v110, s[44:45]
	v_cndmask_b32_e64 v111, 0, v111, s[40:41]
	v_cndmask_b32_e64 v112, 0, v112, s[38:39]
	v_cndmask_b32_e32 v113, 0, v113, vcc
	v_exp_f32_e32 v193, v116
	v_exp_f32_e32 v198, v117
	v_mul_f32_e32 v116, v183, v100
	v_fmac_f32_e32 v248, v183, v100
	v_mul_f32_e32 v100, v183, v101
	v_fmac_f32_e32 v249, v183, v101
	v_mul_f32_e32 v101, v183, v102
	v_fmac_f32_e32 v250, v183, v102
	v_mul_f32_e32 v102, v183, v103
	v_fmac_f32_e32 v247, v183, v103
	v_mul_f32_e32 v103, v183, v104
	v_fmac_f32_e32 v244, v183, v104
	v_mul_f32_e32 v104, v183, v105
	v_fmac_f32_e32 v245, v183, v105
	v_mul_f32_e32 v105, v183, v106
	v_fmac_f32_e32 v246, v183, v106
	v_mul_f32_e32 v106, v183, v107
	v_fmac_f32_e32 v240, v183, v107
	v_mul_f32_e32 v107, v183, v110
	v_mul_f32_e32 v117, v183, v111
	v_exp_f32_e32 v199, v118
	v_exp_f32_e32 v251, v119
	v_mul_f32_e32 v118, v183, v112
	v_fmac_f32_e32 v242, v183, v112
	v_mul_f32_e32 v119, v183, v113
	v_fmac_f32_e32 v243, v183, v113
	v_cvt_pk_bf16_f32 v112, v103, v104
	v_cvt_pk_bf16_f32 v113, v105, v106
	v_cvt_pk_bf16_f32 v128, v107, v117
	ds_read_b64 v[104:105], v239 offset:1024
	ds_read_b64 v[106:107], v239 offset:1056
	ds_read_b64 v[120:121], v238 offset:1280
	ds_read_b64 v[122:123], v238 offset:1312
	ds_read_b64 v[132:133], v237 offset:1536
	ds_read_b64 v[134:135], v237 offset:1568
	ds_read_b64 v[140:141], v236 offset:1792
	ds_read_b64 v[142:143], v236 offset:1824
	v_fmac_f32_e32 v131, v183, v110
	v_fmac_f32_e32 v241, v183, v111
	v_cvt_pk_bf16_f32 v110, v116, v100
	v_cvt_pk_bf16_f32 v111, v101, v102
	v_cvt_pk_bf16_f32 v129, v118, v119
	s_waitcnt lgkmcnt(6)
	v_mfma_f32_16x16x32_bf16 v[100:103], v[104:107], v[96:99], v[60:63]
	v_mfma_f32_16x16x32_bf16 v[104:107], v[104:107], v[110:113], v[56:59]
	s_waitcnt lgkmcnt(4)
	v_mfma_f32_16x16x32_bf16 v[116:119], v[120:123], v[96:99], v[52:55]
	v_mfma_f32_16x16x32_bf16 v[120:123], v[120:123], v[110:113], v[48:51]
	s_waitcnt lgkmcnt(2)
	v_mfma_f32_16x16x32_bf16 v[124:127], v[132:135], v[96:99], v[44:47]
	v_mfma_f32_16x16x32_bf16 v[132:135], v[132:135], v[110:113], v[40:43]
	s_waitcnt lgkmcnt(0)
	v_mfma_f32_16x16x32_bf16 v[136:139], v[140:143], v[96:99], v[36:39]
	ds_read_b64 v[96:97], v239 offset:1088
	ds_read_b64 v[98:99], v239 offset:1120
	ds_read_b64 v[152:153], v238 offset:1344
	ds_read_b64 v[154:155], v238 offset:1376
	ds_read_b64 v[148:149], v237 offset:1600
	ds_read_b64 v[150:151], v237 offset:1632
	ds_read_b64 v[144:145], v236 offset:1856
	ds_read_b64 v[146:147], v236 offset:1888
	v_mfma_f32_16x16x32_bf16 v[140:143], v[140:143], v[110:113], v[32:35]
	v_add_f32_e32 v110, v248, v249
	v_add_f32_e32 v111, v250, v247
	v_add_f32_e32 v110, v110, v111
	ds_bpermute_b32 v111, v233, v247
	ds_bpermute_b32 v112, v233, v234
	v_add_f32_e32 v113, v246, v240
	s_waitcnt lgkmcnt(0)
	v_cndmask_b32_e64 v112, v111, v112, s[36:37]
	v_add_f32_e32 v110, v110, v112
	v_add_f32_e32 v112, v244, v245
	v_add_f32_e32 v112, v112, v113
	ds_bpermute_b32 v113, v233, v240
	s_waitcnt lgkmcnt(0)
	v_cndmask_b32_e64 v111, v113, v111, s[36:37]
	v_add_f32_e32 v111, v112, v111
	ds_write2_b32 v235, v110, v111 offset1:4
	v_add_f32_e32 v111, v242, v243
	ds_bpermute_b32 v242, v233, v243
	v_add_f32_e32 v110, v131, v241
	v_add_f32_e32 v110, v110, v111
	s_waitcnt lgkmcnt(0)
	v_cndmask_b32_e64 v111, v242, v113, s[36:37]
	v_add_f32_e32 v110, v110, v111
	ds_write_b32 v235, v110 offset:32
	v_add_u32_e32 v110, 50, v2
	v_add_u32_e32 v111, 48, v2
	v_cmp_lt_u32_e64 s[38:39], v110, v171
	v_add_u32_e32 v110, 49, v2
	v_add_u32_e32 v2, 51, v2
	v_cmp_lt_u32_e32 vcc, v111, v174
	v_cmp_lt_u32_e64 s[40:41], v2, v171
	v_cmp_lt_u32_e64 s[42:43], v110, v174
	v_cndmask_b32_e64 v111, 0, v130, s[38:39]
	v_cndmask_b32_e32 v110, 0, v115, vcc
	v_cndmask_b32_e64 v2, 0, v114, s[42:43]
	v_cndmask_b32_e64 v3, 0, v3, s[40:41]
	v_pk_mul_f32 v[112:113], v[184:185], v[110:111]
	v_pk_fma_f32 v[114:115], v[184:185], v[110:111], 0 op_sel_hi:[1,1,0]
	v_pk_mul_f32 v[110:111], v[184:185], v[2:3]
	v_cndmask_b32_e64 v130, 0, v198, s[42:43]
	v_cvt_pk_bf16_f32 v110, v112, v110
	v_cvt_pk_bf16_f32 v111, v113, v111
	v_cndmask_b32_e64 v113, 0, v199, s[38:39]
	v_cndmask_b32_e32 v112, 0, v193, vcc
	v_cndmask_b32_e64 v131, 0, v251, s[40:41]
	v_pk_fma_f32 v[2:3], v[184:185], v[2:3], 0 op_sel_hi:[1,1,0]
	v_pk_mul_f32 v[198:199], v[186:187], v[112:113]
	v_pk_fma_f32 v[240:241], v[186:187], v[112:113], v[114:115]
	v_pk_mul_f32 v[112:113], v[186:187], v[130:131]
	v_pk_fma_f32 v[2:3], v[186:187], v[130:131], v[2:3]
	v_cvt_pk_bf16_f32 v130, v198, v112
	v_cvt_pk_bf16_f32 v131, v199, v113
	v_mfma_f32_16x16x32_bf16 v[112:115], v[96:99], v[108:111], v[100:103]
	s_nop 0
	v_mfma_f32_16x16x32_bf16 v[96:99], v[96:99], v[128:131], v[104:107]
	v_mfma_f32_16x16x32_bf16 v[116:119], v[152:155], v[108:111], v[116:119]
	v_mfma_f32_16x16x32_bf16 v[100:103], v[152:155], v[128:131], v[120:123]
	v_mfma_f32_16x16x32_bf16 v[120:123], v[148:151], v[108:111], v[124:127]
	v_mfma_f32_16x16x32_bf16 v[104:107], v[148:151], v[128:131], v[132:135]
	v_mfma_f32_16x16x32_bf16 v[124:127], v[144:147], v[108:111], v[136:139]
	v_mfma_f32_16x16x32_bf16 v[108:111], v[144:147], v[128:131], v[140:143]
	v_add_f32_e64 v128, v240, v2
	v_add_f32_e64 v129, v241, v3
	v_add_f32_e32 v2, v128, v129
	ds_bpermute_b32 v128, v233, v3
	s_waitcnt lgkmcnt(0)
	v_cndmask_b32_e64 v128, v128, v242, s[36:37]
	s_cbranch_execnz .LBB0_229
.LBB0_228:
	s_waitcnt lgkmcnt(7)
	v_mfma_f32_16x16x32_bf16 v[96:99], v[92:95], v[4:7], v[20:23]
	s_waitcnt lgkmcnt(5)
	v_mfma_f32_16x16x32_bf16 v[100:103], v[84:87], v[4:7], v[20:23]
	v_mfma_f32_16x16x32_bf16 v[96:99], v[88:91], v[8:11], v[96:99]
	s_waitcnt lgkmcnt(4)
	v_mfma_f32_16x16x32_bf16 v[100:103], v[80:83], v[8:11], v[100:103]
	s_waitcnt lgkmcnt(3)
	v_mfma_f32_16x16x32_bf16 v[104:107], v[76:79], v[4:7], v[20:23]
	s_nop 3
	v_exp_f32_e32 v108, v96
	v_exp_f32_e32 v109, v97
	v_exp_f32_e32 v110, v98
	v_exp_f32_e32 v111, v99
	v_exp_f32_e32 v112, v100
	v_exp_f32_e32 v113, v101
	s_waitcnt lgkmcnt(2)
	v_mfma_f32_16x16x32_bf16 v[96:99], v[72:75], v[8:11], v[104:107]
	s_nop 2
	v_exp_f32_e32 v104, v102
	v_exp_f32_e32 v105, v103
	s_waitcnt lgkmcnt(1)
	v_mfma_f32_16x16x32_bf16 v[100:103], v[68:71], v[4:7], v[20:23]
	s_nop 0
	v_exp_f32_e32 v106, v96
	v_exp_f32_e32 v107, v97
	v_exp_f32_e32 v115, v98
	v_exp_f32_e32 v114, v99
	s_waitcnt lgkmcnt(0)
	v_mfma_f32_16x16x32_bf16 v[96:99], v[64:67], v[8:11], v[100:103]
	v_mul_f32_e64 v104, v184, v104
	v_mul_f32_e64 v105, v185, v105
	v_mul_f32_e32 v121, v182, v115
	v_fma_f32 v122, v182, v115, 0
	v_mfma_f32_16x16x32_bf16 v[92:95], v[92:95], v[12:15], v[20:23]
	v_mul_f32_e64 v100, v184, v110
	v_mul_f32_e64 v101, v185, v111
	s_nop 0
	v_exp_f32_e32 v97, v97
	v_exp_f32_e32 v2, v96
	v_mfma_f32_16x16x32_bf16 v[84:87], v[84:87], v[12:15], v[20:23]
	v_exp_f32_e32 v3, v98
	v_exp_f32_e32 v96, v99
	v_pk_mul_f32 v[98:99], v[184:185], v[108:109]
	v_mfma_f32_16x16x32_bf16 v[76:79], v[76:79], v[12:15], v[20:23]
	v_mul_f32_e32 v108, v182, v97
	v_add_f32_e32 v109, 0, v98
	v_add_f32_e32 v116, 0, v99
	v_mfma_f32_16x16x32_bf16 v[68:71], v[68:71], v[12:15], v[20:23]
	v_add_f32_e32 v110, 0, v100
	v_add_f32_e32 v111, 0, v101
	v_pk_mul_f32 v[102:103], v[184:185], v[112:113]
	v_mfma_f32_16x16x32_bf16 v[88:91], v[88:91], v[16:19], v[92:95]
	v_add_f32_e32 v117, 0, v104
	v_add_f32_e32 v118, 0, v105
	v_add_f32_e32 v112, 0, v102
	v_mfma_f32_16x16x32_bf16 v[80:83], v[80:83], v[16:19], v[84:87]
	v_cvt_pk_bf16_f32 v92, v98, v99
	v_cvt_pk_bf16_f32 v93, v100, v101
	v_cvt_pk_bf16_f32 v94, v102, v103
	v_mfma_f32_16x16x32_bf16 v[72:75], v[72:75], v[16:19], v[76:79]
	v_exp_f32_e32 v86, v88
	v_exp_f32_e32 v87, v89
	v_cvt_pk_bf16_f32 v95, v104, v105
	v_mfma_f32_16x16x32_bf16 v[64:67], v[64:67], v[16:19], v[68:71]
	v_exp_f32_e32 v76, v90
	v_exp_f32_e32 v78, v80
	v_exp_f32_e32 v79, v81
	v_exp_f32_e32 v80, v82
	v_exp_f32_e32 v81, v83
	v_exp_f32_e32 v82, v72
	v_exp_f32_e32 v83, v73
	v_exp_f32_e32 v85, v74
	v_exp_f32_e32 v115, v75
	v_exp_f32_e32 v88, v64
	v_exp_f32_e32 v90, v65
	v_exp_f32_e32 v89, v66
	v_exp_f32_e32 v97, v67
	ds_read_b64 v[64:65], v239 offset:1024
	ds_read_b64 v[66:67], v239 offset:1056
	ds_read_b64 v[72:73], v238 offset:1280
	ds_read_b64 v[74:75], v238 offset:1312
	v_exp_f32_e32 v77, v91
	v_pk_mul_f32 v[68:69], v[186:187], v[86:87]
	s_waitcnt lgkmcnt(2)
	v_mfma_f32_16x16x32_bf16 v[60:63], v[64:67], v[92:95], v[60:63]
	v_mul_f32_e64 v70, v186, v76
	v_mul_f32_e64 v71, v187, v77
	v_pk_mul_f32 v[76:77], v[186:187], v[78:79]
	v_pk_mul_f32 v[78:79], v[186:187], v[80:81]
	v_add_f32_e32 v86, v109, v68
	v_add_f32_e32 v87, v116, v69
	v_add_f32_e32 v91, v110, v70
	v_add_f32_e32 v98, v111, v71
	v_cvt_pk_bf16_f32 v68, v68, v69
	v_cvt_pk_bf16_f32 v69, v70, v71
	v_cvt_pk_bf16_f32 v70, v76, v77
	v_cvt_pk_bf16_f32 v71, v78, v79
	s_waitcnt lgkmcnt(0)
	v_mfma_f32_16x16x32_bf16 v[52:55], v[72:75], v[92:95], v[52:55]
	v_add_f32_e32 v113, 0, v103
	v_pk_mul_f32 v[106:107], v[184:185], v[106:107]
	v_add_f32_e32 v101, v117, v78
	v_mfma_f32_16x16x32_bf16 v[56:59], v[64:67], v[68:71], v[56:59]
	ds_read_b64 v[64:65], v237 offset:1536
	ds_read_b64 v[66:67], v237 offset:1568
	v_add_f32_e32 v102, v118, v79
	v_pk_mul_f32 v[78:79], v[182:183], v[114:115]
	v_mfma_f32_16x16x32_bf16 v[48:51], v[72:75], v[68:71], v[48:51]
	ds_read_b64 v[72:73], v236 offset:1792
	ds_read_b64 v[74:75], v236 offset:1824
	v_add_f32_e32 v119, 0, v106
	v_add_f32_e32 v120, 0, v107
	s_waitcnt lgkmcnt(2)
	v_mfma_f32_16x16x32_bf16 v[44:47], v[64:67], v[92:95], v[44:47]
	v_add_f32_e32 v99, v112, v76
	v_add_f32_e32 v100, v113, v77
	v_pk_mul_f32 v[76:77], v[186:187], v[82:83]
	v_mfma_f32_16x16x32_bf16 v[40:43], v[64:67], v[68:71], v[40:43]
	ds_bpermute_b32 v66, v233, v234
	v_mul_f32_e32 v80, v183, v85
	v_add_f32_e32 v81, 0, v78
	s_waitcnt lgkmcnt(1)
	v_mfma_f32_16x16x32_bf16 v[36:39], v[72:75], v[92:95], v[36:39]
	ds_bpermute_b32 v94, v233, v98
	v_add_f32_e32 v67, v86, v87
	v_add_f32_e32 v86, v91, v98
	v_add_f32_e32 v103, v119, v76
	v_add_f32_e32 v104, v120, v77
	v_fmac_f32_e32 v122, v183, v85
	v_cvt_pk_bf16_f32 v85, v121, v78
	v_add_f32_e32 v105, v81, v79
	v_cvt_pk_bf16_f32 v64, v76, v77
	v_cvt_pk_bf16_f32 v65, v80, v79
	v_mfma_f32_16x16x32_bf16 v[32:35], v[72:75], v[68:71], v[32:35]
	ds_read_b64 v[68:69], v239 offset:1088
	ds_read_b64 v[70:71], v239 offset:1120
	ds_read_b64 v[72:73], v238 offset:1344
	ds_read_b64 v[74:75], v238 offset:1376
	ds_read_b64 v[76:77], v237 offset:1600
	ds_read_b64 v[78:79], v237 offset:1632
	v_add_f32_e32 v67, v67, v86
	s_waitcnt lgkmcnt(6)
	v_cndmask_b32_e64 v66, v94, v66, s[36:37]
	v_pk_mul_f32 v[92:93], v[182:183], v[96:97]
	v_add_f32_e32 v91, v67, v66
	v_pk_mul_f32 v[66:67], v[184:185], v[2:3]
	v_cvt_pk_bf16_f32 v84, v106, v107
	v_cvt_pk_bf16_f32 v86, v66, v108
	v_pk_mov_b32 v[66:67], v[66:67], v[92:93] op_sel:[1,0]
	ds_read_b64 v[80:81], v236 offset:1856
	ds_read_b64 v[82:83], v236 offset:1888
	v_cvt_pk_bf16_f32 v87, v66, v67
	ds_bpermute_b32 v106, v233, v102
	v_mul_f32_e32 v90, v183, v90
	s_waitcnt lgkmcnt(5)
	v_mfma_f32_16x16x32_bf16 v[116:119], v[72:75], v[84:87], v[52:55]
	v_add_f32_e32 v95, v99, v100
	v_add_f32_e32 v100, v101, v102
	v_mov_b32_e32 v109, v92
	ds_bpermute_b32 v52, v233, v105
	v_mfma_f32_16x16x32_bf16 v[112:115], v[68:71], v[84:87], v[60:63]
	v_add_f32_e32 v53, v103, v104
	s_nop 1
	v_pk_mul_f32 v[60:61], v[186:187], v[88:89]
	s_waitcnt lgkmcnt(2)
	v_mfma_f32_16x16x32_bf16 v[124:127], v[80:83], v[84:87], v[36:39]
	v_cvt_pk_bf16_f32 v66, v60, v90
	v_cvt_pk_bf16_f32 v67, v61, v93
	s_nop 1
	v_mfma_f32_16x16x32_bf16 v[96:99], v[68:71], v[64:67], v[56:59]
	s_nop 2
	v_add_f32_e32 v56, v95, v100
	v_mfma_f32_16x16x32_bf16 v[100:103], v[72:75], v[64:67], v[48:51]
	s_waitcnt lgkmcnt(1)
	v_cndmask_b32_e64 v57, v106, v94, s[36:37]
	v_add_f32_e32 v56, v56, v57
	ds_write2_b32 v235, v91, v56 offset1:4
	v_add_f32_e32 v48, v122, v105
	v_add_f32_e32 v48, v53, v48
	s_waitcnt lgkmcnt(1)
	v_cndmask_b32_e64 v49, v52, v106, s[36:37]
	v_mfma_f32_16x16x32_bf16 v[120:123], v[76:79], v[84:87], v[44:47]
	v_mov_b32_e32 v91, v93
	s_nop 1
	v_add_f32_e32 v44, v48, v49
	ds_write_b32 v235, v44 offset:32
	v_pk_fma_f32 v[44:45], v[184:185], v[2:3], 0 op_sel_hi:[1,1,0]
	v_pk_add_f32 v[2:3], v[108:109], 0 op_sel_hi:[1,0]
	v_mfma_f32_16x16x32_bf16 v[104:107], v[76:79], v[64:67], v[40:43]
	v_add_f32_e64 v2, v2, v90
	v_add_f32_e64 v3, v3, v91
	ds_bpermute_b32 v38, v233, v3
	v_pk_fma_f32 v[36:37], v[186:187], v[88:89], v[44:45]
	v_mfma_f32_16x16x32_bf16 v[108:111], v[80:83], v[64:67], v[32:35]
	s_waitcnt lgkmcnt(0)
	v_cndmask_b32_e64 v128, v38, v52, s[36:37]
	s_nop 0
	v_pk_add_f32 v[32:33], v[36:37], v[2:3]
	s_nop 0
	v_add_f32_e32 v2, v32, v33

.LBB0_238:
	v_mov_b32_e32 v128, v172
	v_readlane_b32 s2, v254, 49
	s_waitcnt lgkmcnt(0)
	s_barrier
	ds_read_b128 v[20:23], v223
	v_readlane_b32 s3, v254, 50
	v_ashrrev_i32_e32 v129, 31, v128
	s_waitcnt vmcnt(1)
	v_mov_b64_e32 v[24:25], s[10:11]
	v_lshl_add_u64 v[2:3], s[2:3], 0, v[128:129]
	v_mad_u64_u32 v[24:25], s[2:3], v2, s23, v[24:25]
	v_mad_i32_i24 v25, v3, s23, v25
	s_mov_b32 s15, s1
	v_readlane_b32 s2, v254, 47
	v_mul_f32_e32 v0, v226, v227
	v_lshl_add_u64 v[2:3], v[24:25], 0, s[14:15]
	v_readlane_b32 s3, v254, 48
	v_mul_f32_e32 v0, 0x3f83d70a, v0
	v_fmamk_f32 v130, v0, 0x3fb8aa3b, v189
	v_lshl_add_u64 v[2:3], s[2:3], 1, v[2:3]
	global_load_ushort v0, v[2:3], off offset:2560
	v_mov_b32_e32 v34, v210
	s_sub_i32 s0, 0x81, s7
	v_xor_b32_e32 v40, 0x80000000, v130
	s_mov_b32 s6, 0
	s_lshr_b32 s7, s0, 1
	v_mov_b32_e32 v41, v40
	v_mov_b32_e32 v42, v40
	v_mov_b32_e32 v43, v40
	s_waitcnt vmcnt(0)
	v_lshlrev_b32_e32 v0, 16, v0
	v_mul_f32_e32 v0, 0xbfb8aa3b, v0
	v_exp_f32_e32 v0, v0
	s_nop 0
	v_add_f32_e32 v0, 1.0, v0
	v_div_scale_f32 v24, s[2:3], v0, v0, 1.0
	v_rcp_f32_e32 v25, v24
	s_nop 0
	v_fma_f32 v26, -v24, v25, 1.0
	v_fmac_f32_e32 v25, v26, v25
	v_div_scale_f32 v26, vcc, 1.0, v0, 1.0
	v_mul_f32_e32 v27, v26, v25
	v_fma_f32 v28, -v24, v27, v26
	v_fmac_f32_e32 v27, v28, v25
	v_fma_f32 v24, -v24, v27, v26
	v_div_fmas_f32 v24, v24, v25, v27
	v_div_fixup_f32 v0, v24, v0, 1.0
	v_pk_mul_f32 v[26:27], v[114:115], v[0:1] op_sel_hi:[1,0]
	v_pk_mul_f32 v[24:25], v[112:113], v[0:1] op_sel_hi:[1,0]
	ds_write_b128 v224, v[24:27]
	v_pk_mul_f32 v[26:27], v[118:119], v[0:1] op_sel_hi:[1,0]
	v_pk_mul_f32 v[24:25], v[116:117], v[0:1] op_sel_hi:[1,0]
	ds_write_b128 v224, v[24:27] offset:1024
	v_pk_mul_f32 v[26:27], v[122:123], v[0:1] op_sel_hi:[1,0]
	v_pk_mul_f32 v[24:25], v[120:121], v[0:1] op_sel_hi:[1,0]
	ds_write_b128 v224, v[24:27] offset:2048
	v_pk_mul_f32 v[26:27], v[126:127], v[0:1] op_sel_hi:[1,0]
	v_pk_mul_f32 v[24:25], v[124:125], v[0:1] op_sel_hi:[1,0]
	global_load_ushort v0, v[2:3], off offset:2566
	ds_write_b128 v224, v[24:27] offset:3072
	v_sub_u32_e32 v118, v172, v211
	v_add_u32_e32 v122, 1, v172
	s_waitcnt vmcnt(0)
	v_lshlrev_b32_e32 v0, 16, v0
	v_mul_f32_e32 v0, 0xbfb8aa3b, v0
	v_exp_f32_e32 v0, v0
	s_nop 0
	v_add_f32_e32 v0, 1.0, v0
	v_div_scale_f32 v24, s[2:3], v0, v0, 1.0
	v_rcp_f32_e32 v25, v24
	v_readlane_b32 s2, v255, 5
	v_readlane_b32 s3, v255, 6
	v_fma_f32 v26, -v24, v25, 1.0
	v_fmac_f32_e32 v25, v26, v25
	v_div_scale_f32 v26, vcc, 1.0, v0, 1.0
	v_mul_f32_e32 v27, v26, v25
	v_fma_f32 v28, -v24, v27, v26
	v_fmac_f32_e32 v27, v28, v25
	v_fma_f32 v24, -v24, v27, v26
	v_div_fmas_f32 v24, v24, v25, v27
	v_div_fixup_f32 v0, v24, v0, 1.0
	v_pk_mul_f32 v[26:27], v[98:99], v[0:1] op_sel_hi:[1,0]
	v_pk_mul_f32 v[24:25], v[96:97], v[0:1] op_sel_hi:[1,0]
	ds_write_b128 v224, v[24:27] offset:4096
	v_pk_mul_f32 v[26:27], v[102:103], v[0:1] op_sel_hi:[1,0]
	v_pk_mul_f32 v[24:25], v[100:101], v[0:1] op_sel_hi:[1,0]
	ds_write_b128 v224, v[24:27] offset:5120
	v_pk_mul_f32 v[26:27], v[106:107], v[0:1] op_sel_hi:[1,0]
	v_pk_mul_f32 v[24:25], v[104:105], v[0:1] op_sel_hi:[1,0]
	ds_write_b128 v224, v[24:27] offset:6144
	v_pk_mul_f32 v[26:27], v[110:111], v[0:1] op_sel_hi:[1,0]
	v_pk_mul_f32 v[24:25], v[108:109], v[0:1] op_sel_hi:[1,0]
	v_mov_b32_e32 v0, v162
	ds_write_b128 v224, v[24:27] offset:7168
	s_nop 0
	v_mov_b32_e32 v227, v130
	s_add_i32 s36, s93, 1
	s_mov_b32 s37, 1
	s_branch .Lattn_slc
.Lattn_ret1:
	v_mov_b32_e32 v68, v56
	v_mov_b32_e32 v69, v57
	v_mov_b32_e32 v70, v58
	v_mov_b32_e32 v71, v59
	v_mov_b32_e32 v56, v60
	v_mov_b32_e32 v57, v61
	v_mov_b32_e32 v58, v62
	v_mov_b32_e32 v59, v63
	v_mov_b32_e32 v60, v68
	v_mov_b32_e32 v61, v69
	v_mov_b32_e32 v62, v70
	v_mov_b32_e32 v63, v71
	v_mov_b32_e32 v114, v112
	v_mov_b32_e32 v115, v113

.LBB0_266:
	s_add_i32 s19, s18, s0
	v_add3_u32 v64, s19, v138, v139
	s_waitcnt lgkmcnt(7)
	ds_read_b128 v[124:127], v64
	s_waitcnt lgkmcnt(7)
	ds_read_b128 v[120:123], v64 offset:64
	s_waitcnt lgkmcnt(7)
	ds_read_b128 v[116:119], v64 offset:2304
	s_waitcnt lgkmcnt(7)
	ds_read_b128 v[96:99], v64 offset:2368
	s_waitcnt lgkmcnt(7)
	ds_read_b128 v[100:103], v64 offset:4608
	s_waitcnt lgkmcnt(7)
	ds_read_b128 v[104:107], v64 offset:4672
	s_waitcnt lgkmcnt(7)
	ds_read_b128 v[108:111], v64 offset:6912
	s_waitcnt lgkmcnt(7)
	ds_read_b128 v[112:115], v64 offset:6976
	s_lshl_b32 s26, s26, 6
	s_add_i32 s26, s26, s2
	v_sub_u32_e32 v64, s26, v3
	v_cmp_lt_u32_e32 vcc, s96, v64
	s_cbranch_vccz .LBB0_271
	s_waitcnt lgkmcnt(7)
	v_mfma_f32_16x16x32_bf16 v[64:67], v[124:127], v[4:7], v[20:23]
	v_add_u32_e32 v76, s26, v140
	v_add_u32_e32 v80, 1, v76
	v_cmp_gt_u32_e64 s[58:59], s22, v76
	s_waitcnt lgkmcnt(6)
	v_mfma_f32_16x16x32_bf16 v[64:67], v[120:123], v[8:11], v[64:67]
	v_cmp_gt_u32_e64 s[56:57], s22, v80
	v_add_u32_e32 v81, 2, v76
	v_add_u32_e32 v82, 3, v76
	s_waitcnt lgkmcnt(5)
	v_mfma_f32_16x16x32_bf16 v[68:71], v[116:119], v[4:7], v[20:23]
	v_cmp_gt_u32_e64 s[60:61], s22, v81
	s_nop 1
	v_exp_f32_e32 v64, v64
	v_exp_f32_e32 v65, v65
	s_waitcnt lgkmcnt(4)
	v_mfma_f32_16x16x32_bf16 v[68:71], v[96:99], v[8:11], v[68:71]
	v_cmp_gt_u32_e64 s[62:63], s22, v82
	v_cndmask_b32_e64 v95, 0, v64, s[58:59]
	v_cndmask_b32_e64 v80, 0, v65, s[56:57]
	v_exp_f32_e32 v64, v66
	v_exp_f32_e32 v65, v67
	s_waitcnt lgkmcnt(3)
	v_mfma_f32_16x16x32_bf16 v[72:75], v[100:103], v[4:7], v[20:23]
	v_add_u32_e32 v83, 16, v76
	v_cndmask_b32_e64 v81, 0, v64, s[60:61]
	v_exp_f32_e32 v64, v68
	v_cndmask_b32_e64 v82, 0, v65, s[62:63]
	v_exp_f32_e32 v65, v69
	v_add_u32_e32 v84, 17, v76
	v_cmp_gt_u32_e64 s[64:65], s22, v83
	v_cmp_gt_u32_e64 s[48:49], s22, v84
	s_waitcnt lgkmcnt(2)
	v_mfma_f32_16x16x32_bf16 v[72:75], v[104:107], v[8:11], v[72:75]
	v_cndmask_b32_e64 v83, 0, v64, s[64:65]
	v_exp_f32_e32 v64, v70
	v_cndmask_b32_e64 v84, 0, v65, s[48:49]
	v_exp_f32_e32 v65, v71
	v_add_u32_e32 v85, 18, v76
	v_add_u32_e32 v86, 19, v76
	v_cmp_gt_u32_e64 s[50:51], s22, v85
	v_cmp_gt_u32_e64 s[52:53], s22, v86
	v_add_u32_e32 v87, 32, v76
	v_add_u32_e32 v88, 33, v76
	v_add_u32_e32 v89, 34, v76
	v_add_u32_e32 v90, 35, v76
	v_add_u32_e32 v91, 48, v76
	v_add_u32_e32 v92, 49, v76
	v_add_u32_e32 v93, 50, v76
	v_add_u32_e32 v94, 51, v76
	s_waitcnt lgkmcnt(1)
	v_mfma_f32_16x16x32_bf16 v[76:79], v[108:111], v[4:7], v[20:23]
	v_cndmask_b32_e64 v85, 0, v64, s[50:51]
	v_exp_f32_e32 v64, v72
	v_cndmask_b32_e64 v86, 0, v65, s[52:53]
	v_exp_f32_e32 v65, v73
	v_cmp_gt_u32_e64 s[54:55], s22, v87
	v_cmp_gt_u32_e64 s[40:41], s22, v88
	s_waitcnt lgkmcnt(0)
	v_mfma_f32_16x16x32_bf16 v[76:79], v[112:115], v[8:11], v[76:79]
	v_cndmask_b32_e64 v87, 0, v64, s[54:55]
	v_exp_f32_e32 v64, v74
	v_cndmask_b32_e64 v88, 0, v65, s[40:41]
	v_exp_f32_e32 v65, v75
	v_cmp_gt_u32_e32 vcc, s22, v89
	v_cmp_gt_u32_e64 s[38:39], s22, v90
	v_cmp_gt_u32_e64 s[46:47], s22, v91
	v_cndmask_b32_e32 v89, 0, v64, vcc
	v_exp_f32_e32 v64, v76
	v_cndmask_b32_e64 v90, 0, v65, s[38:39]
	v_exp_f32_e32 v65, v77
	v_cmp_gt_u32_e64 s[36:37], s22, v92
	v_cndmask_b32_e64 v91, 0, v64, s[46:47]
	v_exp_f32_e32 v64, v78
	v_cndmask_b32_e64 v92, 0, v65, s[36:37]
	v_exp_f32_e32 v65, v79
	v_cmp_gt_u32_e64 s[42:43], s22, v93
	v_cmp_gt_u32_e64 s[44:45], s22, v94
	v_add_f32_e32 v69, v83, v84
	v_cndmask_b32_e64 v93, 0, v64, s[42:43]
	v_cndmask_b32_e64 v94, 0, v65, s[44:45]
	v_add_f32_e32 v64, v95, v80
	v_add_f32_e32 v65, v81, v82
	v_add_f32_e32 v70, v85, v86
	v_add_f32_e32 v68, v64, v65
	v_mfma_f32_16x16x32_bf16 v[64:67], v[124:127], v[12:15], v[20:23]
	v_add_f32_e32 v69, v69, v70
	v_add_f32_e32 v72, v68, v69
	v_add_f32_e32 v68, v87, v88
	v_add_f32_e32 v69, v89, v90
	v_add_f32_e32 v74, v91, v92
	v_add_f32_e32 v75, v93, v94
	v_add_f32_e32 v73, v68, v69
	v_add_f32_e32 v74, v74, v75
	v_add_f32_e32 v73, v73, v74
	v_mfma_f32_16x16x32_bf16 v[64:67], v[120:123], v[16:19], v[64:67]
	v_add_f32_e32 v72, v72, v73
	v_add_f32_e32 v136, v134, v72
	v_add3_u32 v152, s19, v141, v139
	v_mfma_f32_16x16x32_bf16 v[68:71], v[116:119], v[12:15], v[20:23]
	v_add_u32_e32 v185, 0x2800, v152
	s_nop 2
	v_exp_f32_e32 v64, v64
	v_cvt_pk_bf16_f32 v76, v95, v80
	v_mfma_f32_16x16x32_bf16 v[72:75], v[100:103], v[12:15], v[20:23]
	v_cvt_pk_bf16_f32 v77, v81, v82
	v_cvt_pk_bf16_f32 v80, v87, v88
	v_cvt_pk_bf16_f32 v81, v89, v90
	v_mfma_f32_16x16x32_bf16 v[68:71], v[96:99], v[16:19], v[68:71]
	v_cvt_pk_bf16_f32 v82, v91, v92
	ds_read_b64 v[88:89], v185 offset:1280
	ds_read_b64 v[90:91], v185 offset:1312
	v_cndmask_b32_e64 v137, 0, v64, s[58:59]
	v_mfma_f32_16x16x32_bf16 v[72:75], v[104:107], v[16:19], v[72:75]
	v_exp_f32_e32 v64, v65
	v_exp_f32_e32 v65, v66
	v_exp_f32_e32 v66, v67
	s_nop 0
	v_exp_f32_e32 v67, v68
	v_exp_f32_e32 v68, v69
	v_exp_f32_e32 v69, v70
	v_exp_f32_e32 v70, v71
	v_exp_f32_e32 v71, v72
	v_exp_f32_e32 v72, v73
	v_cvt_pk_bf16_f32 v78, v83, v84
	v_cvt_pk_bf16_f32 v79, v85, v86
	v_mfma_f32_16x16x32_bf16 v[84:87], v[108:111], v[12:15], v[20:23]
	v_cndmask_b32_e64 v143, 0, v64, s[56:57]
	v_cndmask_b32_e64 v171, 0, v65, s[60:61]
	v_cndmask_b32_e64 v172, 0, v66, s[62:63]
	v_cndmask_b32_e64 v173, 0, v67, s[64:65]
	v_cndmask_b32_e64 v193, 0, v68, s[48:49]
	v_cndmask_b32_e64 v198, 0, v69, s[50:51]
	v_cndmask_b32_e64 v199, 0, v70, s[52:53]
	v_add_u32_e32 v174, 0x2000, v152
	v_cndmask_b32_e64 v225, 0, v71, s[54:55]
	v_cvt_pk_bf16_f32 v68, v137, v143
	v_cvt_pk_bf16_f32 v69, v171, v172
	v_cvt_pk_bf16_f32 v70, v173, v193
	v_cvt_pk_bf16_f32 v71, v198, v199
	v_add_u32_e32 v226, 0x3000, v152
	v_add_u32_e32 v228, 0x3800, v152
	ds_read_b64 v[64:65], v174 offset:1024
	ds_read_b64 v[66:67], v174 offset:1056
	ds_read_b64 v[144:145], v226 offset:1536
	ds_read_b64 v[146:147], v226 offset:1568
	s_waitcnt lgkmcnt(4)
	v_mfma_f32_16x16x32_bf16 v[148:151], v[88:91], v[76:79], v[52:55]
	v_cndmask_b32_e64 v227, 0, v72, s[40:41]
	v_exp_f32_e32 v176, v74
	v_exp_f32_e32 v177, v75
	v_mfma_f32_16x16x32_bf16 v[72:75], v[88:91], v[68:71], v[48:51]
	ds_read_b64 v[88:89], v228 offset:1792
	ds_read_b64 v[90:91], v228 offset:1824
	v_cndmask_b32_e32 v229, 0, v176, vcc
	v_cndmask_b32_e64 v230, 0, v177, s[38:39]
	v_mfma_f32_16x16x32_bf16 v[84:87], v[112:115], v[16:19], v[84:87]
	ds_read_b64 v[176:177], v174 offset:1088
	ds_read_b64 v[178:179], v174 offset:1120
	v_cvt_pk_bf16_f32 v83, v93, v94
	v_cvt_pk_bf16_f32 v184, v225, v227
	s_waitcnt lgkmcnt(6)
	v_mfma_f32_16x16x32_bf16 v[92:95], v[64:67], v[76:79], v[60:63]
	s_nop 2
	v_exp_f32_e32 v84, v84
	v_mfma_f32_16x16x32_bf16 v[64:67], v[64:67], v[68:71], v[56:59]
	v_cndmask_b32_e64 v231, 0, v84, s[46:47]
	v_exp_f32_e32 v84, v85
	s_waitcnt lgkmcnt(4)
	v_mfma_f32_16x16x32_bf16 v[152:155], v[144:147], v[76:79], v[44:47]
	v_exp_f32_e32 v85, v86
	v_exp_f32_e32 v86, v87
	v_cndmask_b32_e64 v174, 0, v84, s[36:37]
	v_mfma_f32_16x16x32_bf16 v[144:147], v[144:147], v[68:71], v[40:43]
	v_cndmask_b32_e64 v232, 0, v85, s[42:43]
	v_cndmask_b32_e64 v233, 0, v86, s[44:45]
	v_cvt_pk_bf16_f32 v186, v231, v174
	s_waitcnt lgkmcnt(2)
	v_mfma_f32_16x16x32_bf16 v[180:183], v[88:91], v[68:71], v[32:35]
	ds_read_b64 v[68:69], v185 offset:1344
	ds_read_b64 v[70:71], v185 offset:1376
	v_cvt_pk_bf16_f32 v185, v229, v230
	v_cvt_pk_bf16_f32 v187, v232, v233
	s_waitcnt lgkmcnt(2)
	v_mfma_f32_16x16x32_bf16 v[84:87], v[176:179], v[80:83], v[92:95]
	v_mfma_f32_16x16x32_bf16 v[64:67], v[176:179], v[184:187], v[64:67]
	ds_read_b64 v[176:177], v226 offset:1600
	ds_read_b64 v[178:179], v226 offset:1632
	s_nop 0
	v_add_f32_e32 v92, v137, v143
	v_add_f32_e32 v93, v171, v172
	v_mfma_f32_16x16x32_bf16 v[76:79], v[88:91], v[76:79], v[36:39]
	v_add_f32_e32 v92, v92, v93
	v_add_f32_e32 v93, v173, v193
	v_add_f32_e32 v94, v198, v199
	s_waitcnt lgkmcnt(2)
	v_mfma_f32_16x16x32_bf16 v[88:91], v[68:71], v[80:83], v[148:151]
	s_nop 2
	ds_read_b64 v[148:149], v228 offset:1856
	ds_read_b64 v[150:151], v228 offset:1888
	v_mfma_f32_16x16x32_bf16 v[68:71], v[68:71], v[184:187], v[72:75]
	s_nop 2
	v_add_f32_e32 v72, v93, v94
	v_add_f32_e32 v137, v92, v72
	v_add_f32_e32 v72, v225, v227
	v_add_f32_e32 v73, v229, v230
	v_add_f32_e32 v143, v72, v73
	s_waitcnt lgkmcnt(2)
	v_mfma_f32_16x16x32_bf16 v[72:75], v[176:179], v[184:187], v[144:147]
	s_nop 2
	v_add_f32_e32 v144, v231, v174
	v_add_f32_e32 v145, v232, v233
	v_add_f32_e32 v144, v144, v145
	v_mfma_f32_16x16x32_bf16 v[92:95], v[176:179], v[80:83], v[152:155]
	s_waitcnt lgkmcnt(0)
	v_mfma_f32_16x16x32_bf16 v[80:83], v[148:151], v[80:83], v[76:79]
	s_nop 2
	v_add_f32_e32 v76, v143, v144
	v_add_f32_e32 v76, v137, v76
	v_add_f32_e32 v137, v135, v76
	v_mfma_f32_16x16x32_bf16 v[76:79], v[148:151], v[184:187], v[180:183]
	s_cbranch_execnz .LBB0_269
.LBB0_268:
	s_waitcnt lgkmcnt(7)
	v_mfma_f32_16x16x32_bf16 v[64:67], v[124:127], v[4:7], v[20:23]
	s_waitcnt lgkmcnt(5)
	v_mfma_f32_16x16x32_bf16 v[68:71], v[116:119], v[4:7], v[20:23]
	s_waitcnt lgkmcnt(3)
	v_mfma_f32_16x16x32_bf16 v[72:75], v[100:103], v[4:7], v[20:23]
	s_waitcnt lgkmcnt(1)
	v_mfma_f32_16x16x32_bf16 v[76:79], v[108:111], v[4:7], v[20:23]
	v_mfma_f32_16x16x32_bf16 v[64:67], v[120:123], v[8:11], v[64:67]
	v_mfma_f32_16x16x32_bf16 v[68:71], v[96:99], v[8:11], v[68:71]
	v_mfma_f32_16x16x32_bf16 v[72:75], v[104:107], v[8:11], v[72:75]
	s_nop 5
	v_exp_f32_e32 v80, v64
	v_exp_f32_e32 v82, v65
	v_exp_f32_e32 v66, v66
	s_waitcnt lgkmcnt(0)
	v_mfma_f32_16x16x32_bf16 v[76:79], v[112:115], v[8:11], v[76:79]
	v_exp_f32_e32 v84, v67
	v_exp_f32_e32 v81, v68
	v_exp_f32_e32 v83, v69
	v_exp_f32_e32 v67, v70
	v_exp_f32_e32 v85, v71
	v_exp_f32_e32 v68, v72
	v_exp_f32_e32 v70, v73
	v_exp_f32_e32 v72, v74
	v_exp_f32_e32 v74, v75
	v_exp_f32_e32 v69, v76
	v_exp_f32_e32 v71, v77
	v_exp_f32_e32 v73, v78
	v_exp_f32_e32 v75, v79
	v_pk_add_f32 v[64:65], v[80:81], v[82:83]
	v_pk_add_f32 v[76:77], v[66:67], v[84:85]
	v_cvt_pk_bf16_f32 v78, v69, v71
	v_pk_add_f32 v[64:65], v[64:65], v[76:77]
	v_pk_add_f32 v[76:77], v[72:73], v[74:75]
	v_pk_add_f32 v[88:89], v[64:65], v[64:65] op_sel:[0,1] op_sel_hi:[1,0]
	v_pk_add_f32 v[64:65], v[68:69], v[70:71]
	v_cvt_pk_bf16_f32 v67, v67, v85
	v_pk_add_f32 v[64:65], v[64:65], v[76:77]
	v_cvt_pk_bf16_f32 v76, v68, v70
	v_pk_add_f32 v[90:91], v[64:65], v[64:65] op_sel:[0,1] op_sel_hi:[1,0]
	v_cvt_pk_bf16_f32 v64, v80, v82
	v_cvt_pk_bf16_f32 v65, v66, v84
	v_cvt_pk_bf16_f32 v66, v81, v83
	v_mfma_f32_16x16x32_bf16 v[68:71], v[124:127], v[12:15], v[20:23]
	v_cvt_pk_bf16_f32 v77, v72, v74
	v_cvt_pk_bf16_f32 v79, v73, v75
	v_mfma_f32_16x16x32_bf16 v[80:83], v[100:103], v[12:15], v[20:23]
	v_mfma_f32_16x16x32_bf16 v[72:75], v[116:119], v[12:15], v[20:23]
	v_mfma_f32_16x16x32_bf16 v[84:87], v[108:111], v[12:15], v[20:23]
	v_mfma_f32_16x16x32_bf16 v[68:71], v[120:123], v[16:19], v[68:71]
	v_mfma_f32_16x16x32_bf16 v[80:83], v[104:107], v[16:19], v[80:83]
	v_mfma_f32_16x16x32_bf16 v[72:75], v[96:99], v[16:19], v[72:75]
	s_nop 5
	v_exp_f32_e32 v92, v68
	v_exp_f32_e32 v94, v69
	v_exp_f32_e32 v96, v70
	v_mfma_f32_16x16x32_bf16 v[84:87], v[112:115], v[16:19], v[84:87]
	v_exp_f32_e32 v98, v71
	v_exp_f32_e32 v93, v80
	v_exp_f32_e32 v95, v81
	v_exp_f32_e32 v97, v82
	v_exp_f32_e32 v99, v83
	v_exp_f32_e32 v72, v72
	v_exp_f32_e32 v100, v73
	v_exp_f32_e32 v74, v74
	v_exp_f32_e32 v102, v75
	v_exp_f32_e32 v73, v84
	v_exp_f32_e32 v101, v85
	v_exp_f32_e32 v75, v86
	v_exp_f32_e32 v103, v87
	v_pk_add_f32 v[68:69], v[92:93], v[94:95]
	v_pk_add_f32 v[70:71], v[96:97], v[98:99]
	v_cvt_pk_bf16_f32 v97, v97, v99
	v_pk_add_f32 v[68:69], v[68:69], v[70:71]
	v_pk_add_f32 v[70:71], v[72:73], v[100:101]
	v_pk_add_f32 v[80:81], v[74:75], v[102:103]
	v_cvt_pk_bf16_f32 v99, v75, v103
	v_pk_add_f32 v[70:71], v[70:71], v[80:81]
	s_nop 0
	v_pk_add_f32 v[68:69], v[68:69], v[70:71]
	v_cvt_pk_bf16_f32 v70, v72, v100
	v_mov_b32_e32 v89, v68
	v_mov_b32_e32 v91, v69
	v_pk_add_f32 v[68:69], v[88:89], v[90:91]
	v_add3_u32 v88, s19, v142, v139
	v_pk_add_f32 v[136:137], v[134:135], v[68:69]
	v_cvt_pk_bf16_f32 v68, v92, v94
	v_cvt_pk_bf16_f32 v69, v96, v98
	v_cvt_pk_bf16_f32 v96, v93, v95
	v_add_u32_e32 v92, 0x2000, v88
	v_add_u32_e32 v93, 0x2800, v88
	v_add_u32_e32 v94, 0x3000, v88
	v_add_u32_e32 v95, 0x3800, v88
	v_cvt_pk_bf16_f32 v71, v74, v102
	v_cvt_pk_bf16_f32 v98, v73, v101
	ds_read_b64 v[72:73], v92 offset:1024
	ds_read_b64 v[74:75], v92 offset:1056
	ds_read_b64 v[80:81], v93 offset:1280
	ds_read_b64 v[82:83], v93 offset:1312
	ds_read_b64 v[84:85], v94 offset:1536
	ds_read_b64 v[86:87], v94 offset:1568
	ds_read_b64 v[88:89], v95 offset:1792
	ds_read_b64 v[90:91], v95 offset:1824
	s_waitcnt lgkmcnt(6)
	v_mfma_f32_16x16x32_bf16 v[60:63], v[72:75], v[64:67], v[60:63]
	v_mfma_f32_16x16x32_bf16 v[56:59], v[72:75], v[68:71], v[56:59]
	s_waitcnt lgkmcnt(4)
	v_mfma_f32_16x16x32_bf16 v[52:55], v[80:83], v[64:67], v[52:55]
	v_mfma_f32_16x16x32_bf16 v[48:51], v[80:83], v[68:71], v[48:51]
	s_waitcnt lgkmcnt(2)
	v_mfma_f32_16x16x32_bf16 v[44:47], v[84:87], v[64:67], v[44:47]
	v_mfma_f32_16x16x32_bf16 v[40:43], v[84:87], v[68:71], v[40:43]
	s_waitcnt lgkmcnt(0)
	v_mfma_f32_16x16x32_bf16 v[36:39], v[88:91], v[64:67], v[36:39]
	v_mfma_f32_16x16x32_bf16 v[32:35], v[88:91], v[68:71], v[32:35]
	ds_read_b64 v[64:65], v92 offset:1088
	ds_read_b64 v[66:67], v92 offset:1120
	ds_read_b64 v[68:69], v93 offset:1344
	ds_read_b64 v[70:71], v93 offset:1376
	ds_read_b64 v[72:73], v94 offset:1600
	ds_read_b64 v[74:75], v94 offset:1632
	ds_read_b64 v[100:101], v95 offset:1856
	ds_read_b64 v[102:103], v95 offset:1888
	s_waitcnt lgkmcnt(6)
	v_mfma_f32_16x16x32_bf16 v[84:87], v[64:67], v[76:79], v[60:63]
	v_mfma_f32_16x16x32_bf16 v[64:67], v[64:67], v[96:99], v[56:59]
	s_waitcnt lgkmcnt(4)
	v_mfma_f32_16x16x32_bf16 v[88:91], v[68:71], v[76:79], v[52:55]
	v_mfma_f32_16x16x32_bf16 v[68:71], v[68:71], v[96:99], v[48:51]
	s_waitcnt lgkmcnt(2)
	v_mfma_f32_16x16x32_bf16 v[92:95], v[72:75], v[76:79], v[44:47]
	v_mfma_f32_16x16x32_bf16 v[72:75], v[72:75], v[96:99], v[40:43]
	s_waitcnt lgkmcnt(0)
	v_mfma_f32_16x16x32_bf16 v[80:83], v[100:103], v[76:79], v[36:39]
	v_mfma_f32_16x16x32_bf16 v[76:79], v[100:103], v[96:99], v[32:35]
